# remove every s_setprio flip inside the 4 GEMM K-loops (load segments no longer lose VALU/LDS issue arbitration to the MFMA wave) on top of merged waits
# speedup vs baseline: 1.0096x; 1.0067x over previous
; #define PG8_STAGE(bufoff, gbase, voff) do { _Pragma("unroll") for (int _i = 0; _i < 2; ++_i) \
;         __builtin_amdgcn_global_load_lds((const unsigned*)((const char*)(gbase) + (voff)[_i]), (PG8_LAS unsigned*)(lds + (bufoff) + ldsw + _i * 8192), 16, 0, 0); } while (0)
; #define PG8_LDA(dst, b, h) do { _Pragma("unroll") for (int m = 0; m < 4; ++m) _Pragma("unroll") for (int k = 0; k < 2; ++k) dst[m][k] = *(const PG8_LAS bf16x8*)(lds + PG8_SA(b, h) + aoff + m * 2048 + k * 1024); } while (0)
; #define PG8_LDB(dst, b, h) do { _Pragma("unroll") for (int n = 0; n < 2; ++n) _Pragma("unroll") for (int k = 0; k < 2; ++k) dst[n][k] = *(const PG8_LAS bf16x8*)(lds + PG8_SB(b, h) + boff + n * 2048 + k * 1024); } while (0)
; #define PG8_MMA(ai, bj, At, Bt) do { __builtin_amdgcn_s_setprio(1); _Pragma("unroll") for (int m = 0; m < 4; ++m) _Pragma("unroll") for (int n = 0; n < 2; ++n) _Pragma("unroll") for (int k = 0; k < 2; ++k) \
;         acc[ai][bj][m][n] = __builtin_amdgcn_mfma_f32_16x16x32_bf16(Bt[n][k], At[m][k], acc[ai][bj][m][n], 0, 0, 0); __builtin_amdgcn_s_setprio(0); } while (0)
; #define PG8_WAIT_V(n) asm volatile("s_waitcnt vmcnt(" #n ")" ::: "memory")
; #define PG8_WAIT_L(n) asm volatile("s_waitcnt lgkmcnt(" #n ")" ::: "memory")
; #define PG8_BAR __builtin_amdgcn_s_barrier()
; #define PG8_SCHED __builtin_amdgcn_sched_barrier(0)
; template <class Epi, class Sched, bool ALIGN_EPI = false, bool SP2 = false>
; __device__ __forceinline__ void gemm_phase(PG8_LAS unsigned char* lds, const Gemm g, const Sched& S, const Epi& E, int tid_in) {
;     ...
;             const bool last = (t == nt - 2);
;             const char* a1 = cA + (size_t)(t + 1) * kstep;
;             const char* a2 = last ? nA : cA + (size_t)(t + 2) * kstep; const char* b2 = last ? nB : cB + (size_t)(t + 2) * kstep;
;             const char* a3 = a2 + kstep; const char* b3 = b2 + kstep;
;             if (last && has_next) S.a_ready(nxt);
;             if constexpr (SP2) {
;             PG8_LDB(B0, 0, 0); PG8_LDB(B1, 0, 1); PG8_SCHED; PG8_LDA(At, 0, 0); PG8_STAGE(PG8_SA(1, 1), a1 + hstep, voffA);
;             PG8_WAIT_V(8); PG8_WAIT_L(0); PG8_BAR; PG8_MMA(0, 0, At, B0); PG8_MMA(0, 1, At, B1); PG8_BAR; PG8_SCHED;
;             PG8_LDA(At, 0, 1); PG8_STAGE(PG8_SB(0, 0), b2, voffB); PG8_STAGE(PG8_SB(0, 1), b2 + hstep, voffB); PG8_STAGE(PG8_SA(0, 0), a2, voffA);
.LBB0_110:
	s_cmp_eq_u32 s11, 28
	s_cselect_b64 vcc, -1, 0
	s_add_i32 s13, 0, 0x10000
	s_add_i32 s14, 0, 0x14000
	v_lshl_add_u64 v[176:177], v[166:167], 0, s[52:53]
	v_add_u32_e32 v188, s13, v168
	v_add_u32_e32 v204, s14, v168
	v_cndmask_b32_e32 v241, v177, v131, vcc
	v_cndmask_b32_e32 v240, v176, v160, vcc
	ds_read_b128 v[176:179], v188
	ds_read_b128 v[180:183], v188 offset:1024
	ds_read_b128 v[184:187], v188 offset:2048
	ds_read_b128 v[188:191], v188 offset:3072
	ds_read_b128 v[192:195], v204
	ds_read_b128 v[196:199], v204 offset:1024
	ds_read_b128 v[200:203], v204 offset:2048
	ds_read_b128 v[204:207], v204 offset:3072
	v_cndmask_b32_e32 v243, v165, v161, vcc
	v_cndmask_b32_e32 v242, v164, v162, vcc
	v_lshl_add_u64 v[244:245], v[166:167], 0, v[154:155]
	s_add_i32 m0, s18, 0xc000
	ds_read_b128 v[208:211], v175
	ds_read_b128 v[212:215], v175 offset:1024
	ds_read_b128 v[216:219], v175 offset:2048
	ds_read_b128 v[220:223], v175 offset:3072
	ds_read_b128 v[224:227], v175 offset:4096
	ds_read_b128 v[228:231], v175 offset:5120
	ds_read_b128 v[232:235], v175 offset:6144
	ds_read_b128 v[236:239], v175 offset:7168
	global_load_lds_dwordx4 v[244:245], off
	v_lshl_add_u64 v[244:245], v[166:167], 0, v[152:153]
	s_add_i32 m0, s18, 0xe000
	s_nop 0
	global_load_lds_dwordx4 v[244:245], off
	s_waitcnt vmcnt(8) lgkmcnt(0)
	s_barrier
	v_mfma_f32_16x16x32_bf16 v[124:127], v[176:179], v[208:211], v[124:127]
	v_mfma_f32_16x16x32_bf16 v[120:123], v[184:187], v[208:211], v[120:123]
	v_mfma_f32_16x16x32_bf16 v[116:119], v[176:179], v[216:219], v[116:119]
	v_mfma_f32_16x16x32_bf16 v[108:111], v[184:187], v[216:219], v[108:111]
	v_mfma_f32_16x16x32_bf16 v[100:103], v[176:179], v[224:227], v[100:103]
	v_mfma_f32_16x16x32_bf16 v[92:95], v[184:187], v[224:227], v[92:95]
	v_mfma_f32_16x16x32_bf16 v[84:87], v[176:179], v[232:235], v[84:87]
	v_mfma_f32_16x16x32_bf16 v[76:79], v[184:187], v[232:235], v[76:79]
	v_mfma_f32_16x16x32_bf16 v[124:127], v[180:183], v[212:215], v[124:127]
	v_mfma_f32_16x16x32_bf16 v[120:123], v[188:191], v[212:215], v[120:123]
	v_mfma_f32_16x16x32_bf16 v[116:119], v[180:183], v[220:223], v[116:119]
	v_mfma_f32_16x16x32_bf16 v[108:111], v[188:191], v[220:223], v[108:111]
	v_mfma_f32_16x16x32_bf16 v[100:103], v[180:183], v[228:231], v[100:103]
	v_mfma_f32_16x16x32_bf16 v[92:95], v[188:191], v[228:231], v[92:95]
	v_mfma_f32_16x16x32_bf16 v[84:87], v[180:183], v[236:239], v[84:87]
	v_mfma_f32_16x16x32_bf16 v[76:79], v[188:191], v[236:239], v[76:79]
	v_mfma_f32_16x16x32_bf16 v[112:115], v[192:195], v[208:211], v[112:115]
	v_mfma_f32_16x16x32_bf16 v[104:107], v[200:203], v[208:211], v[104:107]
	v_mfma_f32_16x16x32_bf16 v[96:99], v[192:195], v[216:219], v[96:99]
	v_mfma_f32_16x16x32_bf16 v[88:91], v[200:203], v[216:219], v[88:91]
	v_mfma_f32_16x16x32_bf16 v[80:83], v[192:195], v[224:227], v[80:83]
	v_mfma_f32_16x16x32_bf16 v[72:75], v[200:203], v[224:227], v[72:75]
	v_mfma_f32_16x16x32_bf16 v[68:71], v[192:195], v[232:235], v[68:71]
	v_mfma_f32_16x16x32_bf16 v[64:67], v[200:203], v[232:235], v[64:67]
	v_mfma_f32_16x16x32_bf16 v[112:115], v[196:199], v[212:215], v[112:115]
	v_mfma_f32_16x16x32_bf16 v[104:107], v[204:207], v[212:215], v[104:107]
	v_mfma_f32_16x16x32_bf16 v[96:99], v[196:199], v[220:223], v[96:99]
	v_mfma_f32_16x16x32_bf16 v[88:91], v[204:207], v[220:223], v[88:91]
	v_mfma_f32_16x16x32_bf16 v[80:83], v[196:199], v[228:231], v[80:83]
	v_mfma_f32_16x16x32_bf16 v[72:75], v[204:207], v[228:231], v[72:75]
	v_mfma_f32_16x16x32_bf16 v[68:71], v[196:199], v[236:239], v[68:71]
	v_mfma_f32_16x16x32_bf16 v[64:67], v[204:207], v[236:239], v[64:67]
	s_barrier
	s_add_i32 s13, s13, s0
	v_lshl_add_u64 v[244:245], v[242:243], 0, v[128:129]
	s_mov_b32 m0, s13
	ds_read_b128 v[208:211], v175 offset:16384
	ds_read_b128 v[212:215], v175 offset:17408
	ds_read_b128 v[216:219], v175 offset:18432
	ds_read_b128 v[220:223], v175 offset:19456
	ds_read_b128 v[224:227], v175 offset:20480
	ds_read_b128 v[228:231], v175 offset:21504
	ds_read_b128 v[232:235], v175 offset:22528
	ds_read_b128 v[236:239], v175 offset:23552
	global_load_lds_dwordx4 v[244:245], off
	v_lshl_add_u64 v[246:247], v[242:243], 0, v[144:145]
	s_add_i32 m0, s13, 0x2000
	v_lshl_add_u64 v[248:249], v[242:243], 0, s[98:99]
	s_add_i32 s13, s14, s0
	global_load_lds_dwordx4 v[246:247], off
	v_lshl_add_u64 v[250:251], v[248:249], 0, v[128:129]
	s_mov_b32 m0, s13
	v_lshl_add_u64 v[248:249], v[248:249], 0, v[144:145]
	global_load_lds_dwordx4 v[250:251], off
	s_add_i32 m0, s13, 0x2000
	v_lshl_add_u64 v[250:251], v[240:241], 0, v[146:147]
	global_load_lds_dwordx4 v[248:249], off
	v_lshl_add_u64 v[248:249], v[240:241], 0, v[148:149]
	s_mov_b32 m0, s18
	s_nop 0
	global_load_lds_dwordx4 v[248:249], off
	s_mov_b32 m0, s19
	s_nop 0
	global_load_lds_dwordx4 v[250:251], off
	s_waitcnt vmcnt(8) lgkmcnt(0)
	s_barrier
; #define PG8_STAGE(bufoff, gbase, voff) do { _Pragma("unroll") for (int _i = 0; _i < 2; ++_i) \
;         __builtin_amdgcn_global_load_lds((const unsigned*)((const char*)(gbase) + (voff)[_i]), (PG8_LAS unsigned*)(lds + (bufoff) + ldsw + _i * 8192), 16, 0, 0); } while (0)
; #define PG8_LDA(dst, b, h) do { _Pragma("unroll") for (int m = 0; m < 4; ++m) _Pragma("unroll") for (int k = 0; k < 2; ++k) dst[m][k] = *(const PG8_LAS bf16x8*)(lds + PG8_SA(b, h) + aoff + m * 2048 + k * 1024); } while (0)
; #define PG8_LDB(dst, b, h) do { _Pragma("unroll") for (int n = 0; n < 2; ++n) _Pragma("unroll") for (int k = 0; k < 2; ++k) dst[n][k] = *(const PG8_LAS bf16x8*)(lds + PG8_SB(b, h) + boff + n * 2048 + k * 1024); } while (0)
; #define PG8_MMA(ai, bj, At, Bt) do { __builtin_amdgcn_s_setprio(1); _Pragma("unroll") for (int m = 0; m < 4; ++m) _Pragma("unroll") for (int n = 0; n < 2; ++n) _Pragma("unroll") for (int k = 0; k < 2; ++k) \
;         acc[ai][bj][m][n] = __builtin_amdgcn_mfma_f32_16x16x32_bf16(Bt[n][k], At[m][k], acc[ai][bj][m][n], 0, 0, 0); __builtin_amdgcn_s_setprio(0); } while (0)
; #define PG8_WAIT_V(n) asm volatile("s_waitcnt vmcnt(" #n ")" ::: "memory")
; #define PG8_WAIT_L(n) asm volatile("s_waitcnt lgkmcnt(" #n ")" ::: "memory")
; #define PG8_BAR __builtin_amdgcn_s_barrier()
; #define PG8_SCHED __builtin_amdgcn_sched_barrier(0)
; template <class Epi, class Sched, bool ALIGN_EPI = false, bool SP2 = false>
; __device__ __forceinline__ void gemm_phase(PG8_LAS unsigned char* lds, const Gemm g, const Sched& S, const Epi& E, int tid_in) {
;     ...
;             PG8_WAIT_V(8); PG8_WAIT_L(0); PG8_BAR; PG8_MMA(1, 0, At, B0); PG8_MMA(1, 1, At, B1); PG8_BAR; PG8_SCHED;
;             PG8_LDB(B0, 1, 0); PG8_LDB(B1, 1, 1); PG8_SCHED; PG8_LDA(At, 1, 0); PG8_STAGE(PG8_SA(0, 1), a2 + hstep, voffA);
;             PG8_WAIT_V(8); PG8_WAIT_L(0); PG8_BAR; PG8_MMA(0, 0, At, B0); PG8_MMA(0, 1, At, B1); PG8_BAR; PG8_SCHED;
	v_mfma_f32_16x16x32_bf16 v[60:63], v[176:179], v[208:211], v[60:63]
	v_mfma_f32_16x16x32_bf16 v[56:59], v[184:187], v[208:211], v[56:59]
	v_mfma_f32_16x16x32_bf16 v[52:55], v[176:179], v[216:219], v[52:55]
	v_mfma_f32_16x16x32_bf16 v[44:47], v[184:187], v[216:219], v[44:47]
	v_mfma_f32_16x16x32_bf16 v[36:39], v[176:179], v[224:227], v[36:39]
	v_mfma_f32_16x16x32_bf16 v[28:31], v[184:187], v[224:227], v[28:31]
	v_mfma_f32_16x16x32_bf16 v[20:23], v[176:179], v[232:235], v[20:23]
	v_mfma_f32_16x16x32_bf16 v[12:15], v[184:187], v[232:235], v[12:15]
	v_mfma_f32_16x16x32_bf16 v[60:63], v[180:183], v[212:215], v[60:63]
	v_mfma_f32_16x16x32_bf16 v[56:59], v[188:191], v[212:215], v[56:59]
	v_mfma_f32_16x16x32_bf16 v[52:55], v[180:183], v[220:223], v[52:55]
	v_mfma_f32_16x16x32_bf16 v[44:47], v[188:191], v[220:223], v[44:47]
	v_mfma_f32_16x16x32_bf16 v[36:39], v[180:183], v[228:231], v[36:39]
	v_mfma_f32_16x16x32_bf16 v[28:31], v[188:191], v[228:231], v[28:31]
	v_mfma_f32_16x16x32_bf16 v[20:23], v[180:183], v[236:239], v[20:23]
	v_mfma_f32_16x16x32_bf16 v[12:15], v[188:191], v[236:239], v[12:15]
	v_mfma_f32_16x16x32_bf16 v[48:51], v[192:195], v[208:211], v[48:51]
	v_mfma_f32_16x16x32_bf16 v[40:43], v[200:203], v[208:211], v[40:43]
	v_mfma_f32_16x16x32_bf16 v[32:35], v[192:195], v[216:219], v[32:35]
	v_mfma_f32_16x16x32_bf16 v[24:27], v[200:203], v[216:219], v[24:27]
	v_mfma_f32_16x16x32_bf16 v[16:19], v[192:195], v[224:227], v[16:19]
	v_mfma_f32_16x16x32_bf16 v[8:11], v[200:203], v[224:227], v[8:11]
	v_mfma_f32_16x16x32_bf16 v[4:7], v[192:195], v[232:235], v[4:7]
	v_mfma_f32_16x16x32_bf16 v[0:3], v[200:203], v[232:235], v[0:3]
	v_mfma_f32_16x16x32_bf16 v[48:51], v[196:199], v[212:215], v[48:51]
	v_mfma_f32_16x16x32_bf16 v[40:43], v[204:207], v[212:215], v[40:43]
	v_mfma_f32_16x16x32_bf16 v[32:35], v[196:199], v[220:223], v[32:35]
	v_mfma_f32_16x16x32_bf16 v[24:27], v[204:207], v[220:223], v[24:27]
	v_mfma_f32_16x16x32_bf16 v[16:19], v[196:199], v[228:231], v[16:19]
	v_mfma_f32_16x16x32_bf16 v[8:11], v[204:207], v[228:231], v[8:11]
	v_mfma_f32_16x16x32_bf16 v[4:7], v[196:199], v[236:239], v[4:7]
	v_mfma_f32_16x16x32_bf16 v[0:3], v[204:207], v[236:239], v[0:3]
	s_barrier
	s_add_i32 s13, 0, 0x18000
	s_add_i32 s14, 0, 0x1c000
	v_add_u32_e32 v188, s13, v168
	v_add_u32_e32 v204, s14, v168
	ds_read_b128 v[176:179], v188
	ds_read_b128 v[180:183], v188 offset:1024
	ds_read_b128 v[184:187], v188 offset:2048
	ds_read_b128 v[188:191], v188 offset:3072
	ds_read_b128 v[192:195], v204
	ds_read_b128 v[196:199], v204 offset:1024
	ds_read_b128 v[200:203], v204 offset:2048
	ds_read_b128 v[204:207], v204 offset:3072
	v_lshl_add_u64 v[240:241], v[240:241], 0, s[98:99]
	s_mov_b32 m0, s20
	v_lshl_add_u64 v[252:253], v[240:241], 0, v[148:149]
	ds_read_b128 v[208:211], v175 offset:32768
	ds_read_b128 v[212:215], v175 offset:33792
	ds_read_b128 v[216:219], v175 offset:34816
	ds_read_b128 v[220:223], v175 offset:35840
	ds_read_b128 v[224:227], v175 offset:36864
	ds_read_b128 v[228:231], v175 offset:37888
	ds_read_b128 v[232:235], v175 offset:38912
	ds_read_b128 v[236:239], v175 offset:39936
	global_load_lds_dwordx4 v[252:253], off
	v_lshl_add_u64 v[240:241], v[240:241], 0, v[146:147]
	s_mov_b32 m0, s21
	s_nop 0
	global_load_lds_dwordx4 v[240:241], off
	s_waitcnt vmcnt(8) lgkmcnt(0)
	s_barrier
	v_mfma_f32_16x16x32_bf16 v[124:127], v[176:179], v[208:211], v[124:127]
	v_mfma_f32_16x16x32_bf16 v[120:123], v[184:187], v[208:211], v[120:123]
	v_mfma_f32_16x16x32_bf16 v[116:119], v[176:179], v[216:219], v[116:119]
	v_mfma_f32_16x16x32_bf16 v[108:111], v[184:187], v[216:219], v[108:111]
	v_mfma_f32_16x16x32_bf16 v[100:103], v[176:179], v[224:227], v[100:103]
	v_mfma_f32_16x16x32_bf16 v[92:95], v[184:187], v[224:227], v[92:95]
	v_mfma_f32_16x16x32_bf16 v[84:87], v[176:179], v[232:235], v[84:87]
	v_mfma_f32_16x16x32_bf16 v[76:79], v[184:187], v[232:235], v[76:79]
	v_mfma_f32_16x16x32_bf16 v[124:127], v[180:183], v[212:215], v[124:127]
	v_mfma_f32_16x16x32_bf16 v[120:123], v[188:191], v[212:215], v[120:123]
	v_mfma_f32_16x16x32_bf16 v[116:119], v[180:183], v[220:223], v[116:119]
	v_mfma_f32_16x16x32_bf16 v[108:111], v[188:191], v[220:223], v[108:111]
	v_mfma_f32_16x16x32_bf16 v[100:103], v[180:183], v[228:231], v[100:103]
	v_mfma_f32_16x16x32_bf16 v[92:95], v[188:191], v[228:231], v[92:95]
	v_mfma_f32_16x16x32_bf16 v[84:87], v[180:183], v[236:239], v[84:87]
	v_mfma_f32_16x16x32_bf16 v[76:79], v[188:191], v[236:239], v[76:79]
	v_mfma_f32_16x16x32_bf16 v[112:115], v[192:195], v[208:211], v[112:115]
	v_mfma_f32_16x16x32_bf16 v[104:107], v[200:203], v[208:211], v[104:107]
	v_mfma_f32_16x16x32_bf16 v[96:99], v[192:195], v[216:219], v[96:99]
	v_mfma_f32_16x16x32_bf16 v[88:91], v[200:203], v[216:219], v[88:91]
	v_mfma_f32_16x16x32_bf16 v[80:83], v[192:195], v[224:227], v[80:83]
	v_mfma_f32_16x16x32_bf16 v[72:75], v[200:203], v[224:227], v[72:75]
	v_mfma_f32_16x16x32_bf16 v[68:71], v[192:195], v[232:235], v[68:71]
	v_mfma_f32_16x16x32_bf16 v[64:67], v[200:203], v[232:235], v[64:67]
	v_mfma_f32_16x16x32_bf16 v[112:115], v[196:199], v[212:215], v[112:115]
	v_mfma_f32_16x16x32_bf16 v[104:107], v[204:207], v[212:215], v[104:107]
	v_mfma_f32_16x16x32_bf16 v[96:99], v[196:199], v[220:223], v[96:99]
	v_mfma_f32_16x16x32_bf16 v[88:91], v[204:207], v[220:223], v[88:91]
	v_mfma_f32_16x16x32_bf16 v[80:83], v[196:199], v[228:231], v[80:83]
	v_mfma_f32_16x16x32_bf16 v[72:75], v[204:207], v[228:231], v[72:75]
	v_mfma_f32_16x16x32_bf16 v[68:71], v[196:199], v[236:239], v[68:71]
	v_mfma_f32_16x16x32_bf16 v[64:67], v[204:207], v[236:239], v[64:67]
	s_barrier
; #define PG8_STAGE(bufoff, gbase, voff) do { _Pragma("unroll") for (int _i = 0; _i < 2; ++_i) \
;         __builtin_amdgcn_global_load_lds((const unsigned*)((const char*)(gbase) + (voff)[_i]), (PG8_LAS unsigned*)(lds + (bufoff) + ldsw + _i * 8192), 16, 0, 0); } while (0)
; #define PG8_LDA(dst, b, h) do { _Pragma("unroll") for (int m = 0; m < 4; ++m) _Pragma("unroll") for (int k = 0; k < 2; ++k) dst[m][k] = *(const PG8_LAS bf16x8*)(lds + PG8_SA(b, h) + aoff + m * 2048 + k * 1024); } while (0)
; #define PG8_MMA(ai, bj, At, Bt) do { __builtin_amdgcn_s_setprio(1); _Pragma("unroll") for (int m = 0; m < 4; ++m) _Pragma("unroll") for (int n = 0; n < 2; ++n) _Pragma("unroll") for (int k = 0; k < 2; ++k) \
;         acc[ai][bj][m][n] = __builtin_amdgcn_mfma_f32_16x16x32_bf16(Bt[n][k], At[m][k], acc[ai][bj][m][n], 0, 0, 0); __builtin_amdgcn_s_setprio(0); } while (0)
; #define PG8_WAIT_V(n) asm volatile("s_waitcnt vmcnt(" #n ")" ::: "memory")
; #define PG8_WAIT_L(n) asm volatile("s_waitcnt lgkmcnt(" #n ")" ::: "memory")
; #define PG8_BAR __builtin_amdgcn_s_barrier()
; #define PG8_SCHED __builtin_amdgcn_sched_barrier(0)
; template <class Epi, class Sched, bool ALIGN_EPI = false, bool SP2 = false>
; __device__ __forceinline__ void gemm_phase(PG8_LAS unsigned char* lds, const Gemm g, const Sched& S, const Epi& E, int tid_in) {
;     ...
;         for (int t = 0; t < nt; t += 2) {
;             const bool last = (t == nt - 2);
;             const char* a1 = cA + (size_t)(t + 1) * kstep;
;             const char* a2 = last ? nA : cA + (size_t)(t + 2) * kstep; const char* b2 = last ? nB : cB + (size_t)(t + 2) * kstep;
;             const char* a3 = a2 + kstep; const char* b3 = b2 + kstep;
;     ...
;             PG8_LDA(At, 1, 1); PG8_STAGE(PG8_SB(1, 0), b3, voffB); PG8_STAGE(PG8_SB(1, 1), b3 + hstep, voffB); PG8_STAGE(PG8_SA(1, 0), a3, voffA);
;             PG8_WAIT_V(8); PG8_WAIT_L(0); PG8_BAR; PG8_MMA(1, 0, At, B0); PG8_MMA(1, 1, At, B1); PG8_BAR; PG8_SCHED;
;     ...
;         if constexpr (ALIGN_EPI) { if (wr == 0) PG8_BAR; }
	s_add_i32 s13, s13, s0
	v_lshl_add_u64 v[240:241], v[244:245], 0, s[70:71]
	s_mov_b32 m0, s13
	ds_read_b128 v[208:211], v175 offset:49152
	ds_read_b128 v[212:215], v175 offset:50176
	ds_read_b128 v[216:219], v175 offset:51200
	ds_read_b128 v[220:223], v175 offset:52224
	ds_read_b128 v[224:227], v175 offset:53248
	ds_read_b128 v[228:231], v175 offset:54272
	ds_read_b128 v[232:235], v175 offset:55296
	ds_read_b128 v[236:239], v175 offset:56320
	global_load_lds_dwordx4 v[240:241], off
	v_lshl_add_u64 v[240:241], v[246:247], 0, s[70:71]
	s_add_i32 m0, s13, 0x2000
	s_add_i32 s13, s14, s0
	global_load_lds_dwordx4 v[240:241], off
	v_lshl_add_u64 v[240:241], v[242:243], 0, s[86:87]
	v_lshl_add_u64 v[242:243], v[240:241], 0, v[128:129]
	s_mov_b32 m0, s13
	v_lshl_add_u64 v[240:241], v[240:241], 0, v[144:145]
	global_load_lds_dwordx4 v[242:243], off
	s_add_i32 m0, s13, 0x2000
	s_nop 0
	global_load_lds_dwordx4 v[240:241], off
	v_lshl_add_u64 v[240:241], v[248:249], 0, s[70:71]
	s_mov_b32 m0, s22
	s_nop 0
	global_load_lds_dwordx4 v[240:241], off
	v_lshl_add_u64 v[240:241], v[250:251], 0, s[70:71]
	s_mov_b32 m0, s23
	s_nop 0
	global_load_lds_dwordx4 v[240:241], off
	s_waitcnt vmcnt(8) lgkmcnt(0)
	s_barrier
	v_mfma_f32_16x16x32_bf16 v[60:63], v[176:179], v[208:211], v[60:63]
	v_mfma_f32_16x16x32_bf16 v[56:59], v[184:187], v[208:211], v[56:59]
	v_mfma_f32_16x16x32_bf16 v[52:55], v[176:179], v[216:219], v[52:55]
	v_mfma_f32_16x16x32_bf16 v[44:47], v[184:187], v[216:219], v[44:47]
	v_mfma_f32_16x16x32_bf16 v[36:39], v[176:179], v[224:227], v[36:39]
	v_mfma_f32_16x16x32_bf16 v[28:31], v[184:187], v[224:227], v[28:31]
	v_mfma_f32_16x16x32_bf16 v[20:23], v[176:179], v[232:235], v[20:23]
	v_mfma_f32_16x16x32_bf16 v[12:15], v[184:187], v[232:235], v[12:15]
	v_mfma_f32_16x16x32_bf16 v[60:63], v[180:183], v[212:215], v[60:63]
	v_mfma_f32_16x16x32_bf16 v[56:59], v[188:191], v[212:215], v[56:59]
	v_mfma_f32_16x16x32_bf16 v[52:55], v[180:183], v[220:223], v[52:55]
	v_mfma_f32_16x16x32_bf16 v[44:47], v[188:191], v[220:223], v[44:47]
	v_mfma_f32_16x16x32_bf16 v[36:39], v[180:183], v[228:231], v[36:39]
	v_mfma_f32_16x16x32_bf16 v[28:31], v[188:191], v[228:231], v[28:31]
	v_mfma_f32_16x16x32_bf16 v[20:23], v[180:183], v[236:239], v[20:23]
	v_mfma_f32_16x16x32_bf16 v[12:15], v[188:191], v[236:239], v[12:15]
	v_mfma_f32_16x16x32_bf16 v[48:51], v[192:195], v[208:211], v[48:51]
	v_mfma_f32_16x16x32_bf16 v[40:43], v[200:203], v[208:211], v[40:43]
	v_mfma_f32_16x16x32_bf16 v[32:35], v[192:195], v[216:219], v[32:35]
	v_mfma_f32_16x16x32_bf16 v[24:27], v[200:203], v[216:219], v[24:27]
	v_mfma_f32_16x16x32_bf16 v[16:19], v[192:195], v[224:227], v[16:19]
	v_mfma_f32_16x16x32_bf16 v[8:11], v[200:203], v[224:227], v[8:11]
	v_mfma_f32_16x16x32_bf16 v[4:7], v[192:195], v[232:235], v[4:7]
	v_mfma_f32_16x16x32_bf16 v[0:3], v[200:203], v[232:235], v[0:3]
	v_mfma_f32_16x16x32_bf16 v[48:51], v[196:199], v[212:215], v[48:51]
	v_mfma_f32_16x16x32_bf16 v[40:43], v[204:207], v[212:215], v[40:43]
	v_mfma_f32_16x16x32_bf16 v[32:35], v[196:199], v[220:223], v[32:35]
	v_mfma_f32_16x16x32_bf16 v[24:27], v[204:207], v[220:223], v[24:27]
	v_mfma_f32_16x16x32_bf16 v[16:19], v[196:199], v[228:231], v[16:19]
	v_mfma_f32_16x16x32_bf16 v[8:11], v[204:207], v[228:231], v[8:11]
	v_mfma_f32_16x16x32_bf16 v[4:7], v[196:199], v[236:239], v[4:7]
	v_mfma_f32_16x16x32_bf16 v[0:3], v[204:207], v[236:239], v[0:3]
	s_barrier
	s_add_i32 s11, s11, 2
	v_lshl_add_u64 v[164:165], v[164:165], 0, s[82:83]
	s_cmp_gt_u32 s11, 29
	v_lshl_add_u64 v[166:167], v[166:167], 0, s[82:83]
	s_cbranch_scc0 .LBB0_110
	s_and_b64 vcc, exec, s[8:9]
	s_cbranch_vccz .LBB0_113
	s_barrier

; #define PG8_STAGE(bufoff, gbase, voff) do { _Pragma("unroll") for (int _i = 0; _i < 2; ++_i) \
;         __builtin_amdgcn_global_load_lds((const unsigned*)((const char*)(gbase) + (voff)[_i]), (PG8_LAS unsigned*)(lds + (bufoff) + ldsw + _i * 8192), 16, 0, 0); } while (0)
; #define PG8_LDA(dst, b, h) do { _Pragma("unroll") for (int m = 0; m < 4; ++m) _Pragma("unroll") for (int k = 0; k < 2; ++k) dst[m][k] = *(const PG8_LAS bf16x8*)(lds + PG8_SA(b, h) + aoff + m * 2048 + k * 1024); } while (0)
; #define PG8_LDB(dst, b, h) do { _Pragma("unroll") for (int n = 0; n < 2; ++n) _Pragma("unroll") for (int k = 0; k < 2; ++k) dst[n][k] = *(const PG8_LAS bf16x8*)(lds + PG8_SB(b, h) + boff + n * 2048 + k * 1024); } while (0)
; #define PG8_MMA(ai, bj, At, Bt) do { __builtin_amdgcn_s_setprio(1); _Pragma("unroll") for (int m = 0; m < 4; ++m) _Pragma("unroll") for (int n = 0; n < 2; ++n) _Pragma("unroll") for (int k = 0; k < 2; ++k) \
;         acc[ai][bj][m][n] = __builtin_amdgcn_mfma_f32_16x16x32_bf16(Bt[n][k], At[m][k], acc[ai][bj][m][n], 0, 0, 0); __builtin_amdgcn_s_setprio(0); } while (0)
; #define PG8_WAIT_V(n) asm volatile("s_waitcnt vmcnt(" #n ")" ::: "memory")
; #define PG8_WAIT_L(n) asm volatile("s_waitcnt lgkmcnt(" #n ")" ::: "memory")
; #define PG8_BAR __builtin_amdgcn_s_barrier()
; #define PG8_SCHED __builtin_amdgcn_sched_barrier(0)
; template <class Epi, class Sched, bool ALIGN_EPI = false, bool SP2 = false>
; __device__ __forceinline__ void gemm_phase(PG8_LAS unsigned char* lds, const Gemm g, const Sched& S, const Epi& E, int tid_in) {
;     ...
;             const bool last = (t == nt - 2);
;             const char* a1 = cA + (size_t)(t + 1) * kstep;
;             const char* a2 = last ? nA : cA + (size_t)(t + 2) * kstep; const char* b2 = last ? nB : cB + (size_t)(t + 2) * kstep;
;             const char* a3 = a2 + kstep; const char* b3 = b2 + kstep;
;             if (last && has_next) S.a_ready(nxt);
;             if constexpr (SP2) {
;             PG8_LDB(B0, 0, 0); PG8_LDB(B1, 0, 1); PG8_SCHED; PG8_LDA(At, 0, 0); PG8_STAGE(PG8_SA(1, 1), a1 + hstep, voffA);
;             PG8_WAIT_V(8); PG8_WAIT_L(0); PG8_BAR; PG8_MMA(0, 0, At, B0); PG8_MMA(0, 1, At, B1); PG8_BAR; PG8_SCHED;
;             PG8_LDA(At, 0, 1); PG8_STAGE(PG8_SB(0, 0), b2, voffB); PG8_STAGE(PG8_SB(0, 1), b2 + hstep, voffB); PG8_STAGE(PG8_SA(0, 0), a2, voffA);
.LBB0_405:
	s_cmp_eq_u32 s2, 28
	s_cselect_b64 vcc, -1, 0
	s_add_i32 s3, 0, 0x10000
	s_add_i32 s13, 0, 0x14000
	v_lshl_add_u64 v[176:177], v[166:167], 0, s[52:53]
	v_add_u32_e32 v188, s3, v168
	v_add_u32_e32 v204, s13, v168
	v_cndmask_b32_e32 v241, v177, v131, vcc
	v_cndmask_b32_e32 v240, v176, v160, vcc
	ds_read_b128 v[176:179], v188
	ds_read_b128 v[180:183], v188 offset:1024
	ds_read_b128 v[184:187], v188 offset:2048
	ds_read_b128 v[188:191], v188 offset:3072
	ds_read_b128 v[192:195], v204
	ds_read_b128 v[196:199], v204 offset:1024
	ds_read_b128 v[200:203], v204 offset:2048
	ds_read_b128 v[204:207], v204 offset:3072
	v_cndmask_b32_e32 v243, v165, v161, vcc
	v_cndmask_b32_e32 v242, v164, v162, vcc
	v_lshl_add_u64 v[244:245], v[166:167], 0, v[154:155]
	s_add_i32 m0, s16, 0xc000
	ds_read_b128 v[208:211], v175
	ds_read_b128 v[212:215], v175 offset:1024
	ds_read_b128 v[216:219], v175 offset:2048
	ds_read_b128 v[220:223], v175 offset:3072
	ds_read_b128 v[224:227], v175 offset:4096
	ds_read_b128 v[228:231], v175 offset:5120
	ds_read_b128 v[232:235], v175 offset:6144
	ds_read_b128 v[236:239], v175 offset:7168
	global_load_lds_dwordx4 v[244:245], off
	v_lshl_add_u64 v[244:245], v[166:167], 0, v[152:153]
	s_add_i32 m0, s16, 0xe000
	s_nop 0
	global_load_lds_dwordx4 v[244:245], off
	s_waitcnt vmcnt(8) lgkmcnt(0)
	s_barrier
	v_mfma_f32_16x16x32_bf16 v[124:127], v[176:179], v[208:211], v[124:127]
	v_mfma_f32_16x16x32_bf16 v[120:123], v[184:187], v[208:211], v[120:123]
	v_mfma_f32_16x16x32_bf16 v[116:119], v[176:179], v[216:219], v[116:119]
	v_mfma_f32_16x16x32_bf16 v[108:111], v[184:187], v[216:219], v[108:111]
	v_mfma_f32_16x16x32_bf16 v[100:103], v[176:179], v[224:227], v[100:103]
	v_mfma_f32_16x16x32_bf16 v[92:95], v[184:187], v[224:227], v[92:95]
	v_mfma_f32_16x16x32_bf16 v[84:87], v[176:179], v[232:235], v[84:87]
	v_mfma_f32_16x16x32_bf16 v[76:79], v[184:187], v[232:235], v[76:79]
	v_mfma_f32_16x16x32_bf16 v[124:127], v[180:183], v[212:215], v[124:127]
	v_mfma_f32_16x16x32_bf16 v[120:123], v[188:191], v[212:215], v[120:123]
	v_mfma_f32_16x16x32_bf16 v[116:119], v[180:183], v[220:223], v[116:119]
	v_mfma_f32_16x16x32_bf16 v[108:111], v[188:191], v[220:223], v[108:111]
	v_mfma_f32_16x16x32_bf16 v[100:103], v[180:183], v[228:231], v[100:103]
	v_mfma_f32_16x16x32_bf16 v[92:95], v[188:191], v[228:231], v[92:95]
	v_mfma_f32_16x16x32_bf16 v[84:87], v[180:183], v[236:239], v[84:87]
	v_mfma_f32_16x16x32_bf16 v[76:79], v[188:191], v[236:239], v[76:79]
	v_mfma_f32_16x16x32_bf16 v[112:115], v[192:195], v[208:211], v[112:115]
	v_mfma_f32_16x16x32_bf16 v[104:107], v[200:203], v[208:211], v[104:107]
	v_mfma_f32_16x16x32_bf16 v[96:99], v[192:195], v[216:219], v[96:99]
	v_mfma_f32_16x16x32_bf16 v[88:91], v[200:203], v[216:219], v[88:91]
	v_mfma_f32_16x16x32_bf16 v[80:83], v[192:195], v[224:227], v[80:83]
	v_mfma_f32_16x16x32_bf16 v[72:75], v[200:203], v[224:227], v[72:75]
	v_mfma_f32_16x16x32_bf16 v[68:71], v[192:195], v[232:235], v[68:71]
	v_mfma_f32_16x16x32_bf16 v[64:67], v[200:203], v[232:235], v[64:67]
	v_mfma_f32_16x16x32_bf16 v[112:115], v[196:199], v[212:215], v[112:115]
	v_mfma_f32_16x16x32_bf16 v[104:107], v[204:207], v[212:215], v[104:107]
	v_mfma_f32_16x16x32_bf16 v[96:99], v[196:199], v[220:223], v[96:99]
	v_mfma_f32_16x16x32_bf16 v[88:91], v[204:207], v[220:223], v[88:91]
	v_mfma_f32_16x16x32_bf16 v[80:83], v[196:199], v[228:231], v[80:83]
	v_mfma_f32_16x16x32_bf16 v[72:75], v[204:207], v[228:231], v[72:75]
	v_mfma_f32_16x16x32_bf16 v[68:71], v[196:199], v[236:239], v[68:71]
	v_mfma_f32_16x16x32_bf16 v[64:67], v[204:207], v[236:239], v[64:67]
	s_barrier
	s_add_i32 s3, s3, s1
	v_lshl_add_u64 v[244:245], v[242:243], 0, v[128:129]
	s_mov_b32 m0, s3
	ds_read_b128 v[208:211], v175 offset:16384
	ds_read_b128 v[212:215], v175 offset:17408
	ds_read_b128 v[216:219], v175 offset:18432
	ds_read_b128 v[220:223], v175 offset:19456
	ds_read_b128 v[224:227], v175 offset:20480
	ds_read_b128 v[228:231], v175 offset:21504
	ds_read_b128 v[232:235], v175 offset:22528
	ds_read_b128 v[236:239], v175 offset:23552
	global_load_lds_dwordx4 v[244:245], off
	v_lshl_add_u64 v[246:247], v[242:243], 0, v[144:145]
	s_add_i32 m0, s3, 0x2000
	v_lshl_add_u64 v[248:249], v[242:243], 0, s[98:99]
	s_add_i32 s3, s13, s1
	global_load_lds_dwordx4 v[246:247], off
	v_lshl_add_u64 v[250:251], v[248:249], 0, v[128:129]
	s_mov_b32 m0, s3
	v_lshl_add_u64 v[248:249], v[248:249], 0, v[144:145]
	global_load_lds_dwordx4 v[250:251], off
	s_add_i32 m0, s3, 0x2000
	v_lshl_add_u64 v[250:251], v[240:241], 0, v[146:147]
	global_load_lds_dwordx4 v[248:249], off
	v_lshl_add_u64 v[248:249], v[240:241], 0, v[148:149]
	s_mov_b32 m0, s16
	s_nop 0
	global_load_lds_dwordx4 v[248:249], off
	s_mov_b32 m0, s17
	s_nop 0
	global_load_lds_dwordx4 v[250:251], off
	s_waitcnt vmcnt(8) lgkmcnt(0)
	s_barrier
; #define PG8_STAGE(bufoff, gbase, voff) do { _Pragma("unroll") for (int _i = 0; _i < 2; ++_i) \
;         __builtin_amdgcn_global_load_lds((const unsigned*)((const char*)(gbase) + (voff)[_i]), (PG8_LAS unsigned*)(lds + (bufoff) + ldsw + _i * 8192), 16, 0, 0); } while (0)
; #define PG8_LDA(dst, b, h) do { _Pragma("unroll") for (int m = 0; m < 4; ++m) _Pragma("unroll") for (int k = 0; k < 2; ++k) dst[m][k] = *(const PG8_LAS bf16x8*)(lds + PG8_SA(b, h) + aoff + m * 2048 + k * 1024); } while (0)
; #define PG8_LDB(dst, b, h) do { _Pragma("unroll") for (int n = 0; n < 2; ++n) _Pragma("unroll") for (int k = 0; k < 2; ++k) dst[n][k] = *(const PG8_LAS bf16x8*)(lds + PG8_SB(b, h) + boff + n * 2048 + k * 1024); } while (0)
; #define PG8_MMA(ai, bj, At, Bt) do { __builtin_amdgcn_s_setprio(1); _Pragma("unroll") for (int m = 0; m < 4; ++m) _Pragma("unroll") for (int n = 0; n < 2; ++n) _Pragma("unroll") for (int k = 0; k < 2; ++k) \
;         acc[ai][bj][m][n] = __builtin_amdgcn_mfma_f32_16x16x32_bf16(Bt[n][k], At[m][k], acc[ai][bj][m][n], 0, 0, 0); __builtin_amdgcn_s_setprio(0); } while (0)
; #define PG8_WAIT_V(n) asm volatile("s_waitcnt vmcnt(" #n ")" ::: "memory")
; #define PG8_WAIT_L(n) asm volatile("s_waitcnt lgkmcnt(" #n ")" ::: "memory")
; #define PG8_BAR __builtin_amdgcn_s_barrier()
; #define PG8_SCHED __builtin_amdgcn_sched_barrier(0)
; template <class Epi, class Sched, bool ALIGN_EPI = false, bool SP2 = false>
; __device__ __forceinline__ void gemm_phase(PG8_LAS unsigned char* lds, const Gemm g, const Sched& S, const Epi& E, int tid_in) {
;     ...
;             PG8_WAIT_V(8); PG8_WAIT_L(0); PG8_BAR; PG8_MMA(1, 0, At, B0); PG8_MMA(1, 1, At, B1); PG8_BAR; PG8_SCHED;
;             PG8_LDB(B0, 1, 0); PG8_LDB(B1, 1, 1); PG8_SCHED; PG8_LDA(At, 1, 0); PG8_STAGE(PG8_SA(0, 1), a2 + hstep, voffA);
;             PG8_WAIT_V(8); PG8_WAIT_L(0); PG8_BAR; PG8_MMA(0, 0, At, B0); PG8_MMA(0, 1, At, B1); PG8_BAR; PG8_SCHED;
	v_mfma_f32_16x16x32_bf16 v[60:63], v[176:179], v[208:211], v[60:63]
	v_mfma_f32_16x16x32_bf16 v[56:59], v[184:187], v[208:211], v[56:59]
	v_mfma_f32_16x16x32_bf16 v[52:55], v[176:179], v[216:219], v[52:55]
	v_mfma_f32_16x16x32_bf16 v[44:47], v[184:187], v[216:219], v[44:47]
	v_mfma_f32_16x16x32_bf16 v[36:39], v[176:179], v[224:227], v[36:39]
	v_mfma_f32_16x16x32_bf16 v[28:31], v[184:187], v[224:227], v[28:31]
	v_mfma_f32_16x16x32_bf16 v[20:23], v[176:179], v[232:235], v[20:23]
	v_mfma_f32_16x16x32_bf16 v[12:15], v[184:187], v[232:235], v[12:15]
	v_mfma_f32_16x16x32_bf16 v[60:63], v[180:183], v[212:215], v[60:63]
	v_mfma_f32_16x16x32_bf16 v[56:59], v[188:191], v[212:215], v[56:59]
	v_mfma_f32_16x16x32_bf16 v[52:55], v[180:183], v[220:223], v[52:55]
	v_mfma_f32_16x16x32_bf16 v[44:47], v[188:191], v[220:223], v[44:47]
	v_mfma_f32_16x16x32_bf16 v[36:39], v[180:183], v[228:231], v[36:39]
	v_mfma_f32_16x16x32_bf16 v[28:31], v[188:191], v[228:231], v[28:31]
	v_mfma_f32_16x16x32_bf16 v[20:23], v[180:183], v[236:239], v[20:23]
	v_mfma_f32_16x16x32_bf16 v[12:15], v[188:191], v[236:239], v[12:15]
	v_mfma_f32_16x16x32_bf16 v[48:51], v[192:195], v[208:211], v[48:51]
	v_mfma_f32_16x16x32_bf16 v[40:43], v[200:203], v[208:211], v[40:43]
	v_mfma_f32_16x16x32_bf16 v[32:35], v[192:195], v[216:219], v[32:35]
	v_mfma_f32_16x16x32_bf16 v[24:27], v[200:203], v[216:219], v[24:27]
	v_mfma_f32_16x16x32_bf16 v[16:19], v[192:195], v[224:227], v[16:19]
	v_mfma_f32_16x16x32_bf16 v[8:11], v[200:203], v[224:227], v[8:11]
	v_mfma_f32_16x16x32_bf16 v[4:7], v[192:195], v[232:235], v[4:7]
	v_mfma_f32_16x16x32_bf16 v[0:3], v[200:203], v[232:235], v[0:3]
	v_mfma_f32_16x16x32_bf16 v[48:51], v[196:199], v[212:215], v[48:51]
	v_mfma_f32_16x16x32_bf16 v[40:43], v[204:207], v[212:215], v[40:43]
	v_mfma_f32_16x16x32_bf16 v[32:35], v[196:199], v[220:223], v[32:35]
	v_mfma_f32_16x16x32_bf16 v[24:27], v[204:207], v[220:223], v[24:27]
	v_mfma_f32_16x16x32_bf16 v[16:19], v[196:199], v[228:231], v[16:19]
	v_mfma_f32_16x16x32_bf16 v[8:11], v[204:207], v[228:231], v[8:11]
	v_mfma_f32_16x16x32_bf16 v[4:7], v[196:199], v[236:239], v[4:7]
	v_mfma_f32_16x16x32_bf16 v[0:3], v[204:207], v[236:239], v[0:3]
	s_barrier
	s_add_i32 s3, 0, 0x18000
	s_add_i32 s13, 0, 0x1c000
	v_add_u32_e32 v188, s3, v168
	v_add_u32_e32 v204, s13, v168
	ds_read_b128 v[176:179], v188
	ds_read_b128 v[180:183], v188 offset:1024
	ds_read_b128 v[184:187], v188 offset:2048
	ds_read_b128 v[188:191], v188 offset:3072
	ds_read_b128 v[192:195], v204
	ds_read_b128 v[196:199], v204 offset:1024
	ds_read_b128 v[200:203], v204 offset:2048
	ds_read_b128 v[204:207], v204 offset:3072
	v_lshl_add_u64 v[240:241], v[240:241], 0, s[98:99]
	s_mov_b32 m0, s18
	v_lshl_add_u64 v[252:253], v[240:241], 0, v[148:149]
	ds_read_b128 v[208:211], v175 offset:32768
	ds_read_b128 v[212:215], v175 offset:33792
	ds_read_b128 v[216:219], v175 offset:34816
	ds_read_b128 v[220:223], v175 offset:35840
	ds_read_b128 v[224:227], v175 offset:36864
	ds_read_b128 v[228:231], v175 offset:37888
	ds_read_b128 v[232:235], v175 offset:38912
	ds_read_b128 v[236:239], v175 offset:39936
	global_load_lds_dwordx4 v[252:253], off
	v_lshl_add_u64 v[240:241], v[240:241], 0, v[146:147]
	s_mov_b32 m0, s19
	s_nop 0
	global_load_lds_dwordx4 v[240:241], off
	s_waitcnt vmcnt(8) lgkmcnt(0)
	s_barrier
	v_mfma_f32_16x16x32_bf16 v[124:127], v[176:179], v[208:211], v[124:127]
	v_mfma_f32_16x16x32_bf16 v[120:123], v[184:187], v[208:211], v[120:123]
	v_mfma_f32_16x16x32_bf16 v[116:119], v[176:179], v[216:219], v[116:119]
	v_mfma_f32_16x16x32_bf16 v[108:111], v[184:187], v[216:219], v[108:111]
	v_mfma_f32_16x16x32_bf16 v[100:103], v[176:179], v[224:227], v[100:103]
	v_mfma_f32_16x16x32_bf16 v[92:95], v[184:187], v[224:227], v[92:95]
	v_mfma_f32_16x16x32_bf16 v[84:87], v[176:179], v[232:235], v[84:87]
	v_mfma_f32_16x16x32_bf16 v[76:79], v[184:187], v[232:235], v[76:79]
	v_mfma_f32_16x16x32_bf16 v[124:127], v[180:183], v[212:215], v[124:127]
	v_mfma_f32_16x16x32_bf16 v[120:123], v[188:191], v[212:215], v[120:123]
	v_mfma_f32_16x16x32_bf16 v[116:119], v[180:183], v[220:223], v[116:119]
	v_mfma_f32_16x16x32_bf16 v[108:111], v[188:191], v[220:223], v[108:111]
	v_mfma_f32_16x16x32_bf16 v[100:103], v[180:183], v[228:231], v[100:103]
	v_mfma_f32_16x16x32_bf16 v[92:95], v[188:191], v[228:231], v[92:95]
	v_mfma_f32_16x16x32_bf16 v[84:87], v[180:183], v[236:239], v[84:87]
	v_mfma_f32_16x16x32_bf16 v[76:79], v[188:191], v[236:239], v[76:79]
	v_mfma_f32_16x16x32_bf16 v[112:115], v[192:195], v[208:211], v[112:115]
	v_mfma_f32_16x16x32_bf16 v[104:107], v[200:203], v[208:211], v[104:107]
	v_mfma_f32_16x16x32_bf16 v[96:99], v[192:195], v[216:219], v[96:99]
	v_mfma_f32_16x16x32_bf16 v[88:91], v[200:203], v[216:219], v[88:91]
	v_mfma_f32_16x16x32_bf16 v[80:83], v[192:195], v[224:227], v[80:83]
	v_mfma_f32_16x16x32_bf16 v[72:75], v[200:203], v[224:227], v[72:75]
	v_mfma_f32_16x16x32_bf16 v[68:71], v[192:195], v[232:235], v[68:71]
	v_mfma_f32_16x16x32_bf16 v[64:67], v[200:203], v[232:235], v[64:67]
	v_mfma_f32_16x16x32_bf16 v[112:115], v[196:199], v[212:215], v[112:115]
	v_mfma_f32_16x16x32_bf16 v[104:107], v[204:207], v[212:215], v[104:107]
	v_mfma_f32_16x16x32_bf16 v[96:99], v[196:199], v[220:223], v[96:99]
	v_mfma_f32_16x16x32_bf16 v[88:91], v[204:207], v[220:223], v[88:91]
	v_mfma_f32_16x16x32_bf16 v[80:83], v[196:199], v[228:231], v[80:83]
	v_mfma_f32_16x16x32_bf16 v[72:75], v[204:207], v[228:231], v[72:75]
	v_mfma_f32_16x16x32_bf16 v[68:71], v[196:199], v[236:239], v[68:71]
	v_mfma_f32_16x16x32_bf16 v[64:67], v[204:207], v[236:239], v[64:67]
	s_barrier
; #define PG8_STAGE(bufoff, gbase, voff) do { _Pragma("unroll") for (int _i = 0; _i < 2; ++_i) \
;         __builtin_amdgcn_global_load_lds((const unsigned*)((const char*)(gbase) + (voff)[_i]), (PG8_LAS unsigned*)(lds + (bufoff) + ldsw + _i * 8192), 16, 0, 0); } while (0)
; #define PG8_LDA(dst, b, h) do { _Pragma("unroll") for (int m = 0; m < 4; ++m) _Pragma("unroll") for (int k = 0; k < 2; ++k) dst[m][k] = *(const PG8_LAS bf16x8*)(lds + PG8_SA(b, h) + aoff + m * 2048 + k * 1024); } while (0)
; #define PG8_MMA(ai, bj, At, Bt) do { __builtin_amdgcn_s_setprio(1); _Pragma("unroll") for (int m = 0; m < 4; ++m) _Pragma("unroll") for (int n = 0; n < 2; ++n) _Pragma("unroll") for (int k = 0; k < 2; ++k) \
;         acc[ai][bj][m][n] = __builtin_amdgcn_mfma_f32_16x16x32_bf16(Bt[n][k], At[m][k], acc[ai][bj][m][n], 0, 0, 0); __builtin_amdgcn_s_setprio(0); } while (0)
; #define PG8_WAIT_V(n) asm volatile("s_waitcnt vmcnt(" #n ")" ::: "memory")
; #define PG8_WAIT_L(n) asm volatile("s_waitcnt lgkmcnt(" #n ")" ::: "memory")
; #define PG8_BAR __builtin_amdgcn_s_barrier()
; #define PG8_SCHED __builtin_amdgcn_sched_barrier(0)
; template <class Epi, class Sched, bool ALIGN_EPI = false, bool SP2 = false>
; __device__ __forceinline__ void gemm_phase(PG8_LAS unsigned char* lds, const Gemm g, const Sched& S, const Epi& E, int tid_in) {
;     ...
;         for (int t = 0; t < nt; t += 2) {
;             const bool last = (t == nt - 2);
;             const char* a1 = cA + (size_t)(t + 1) * kstep;
;             const char* a2 = last ? nA : cA + (size_t)(t + 2) * kstep; const char* b2 = last ? nB : cB + (size_t)(t + 2) * kstep;
;             const char* a3 = a2 + kstep; const char* b3 = b2 + kstep;
;     ...
;             PG8_LDA(At, 1, 1); PG8_STAGE(PG8_SB(1, 0), b3, voffB); PG8_STAGE(PG8_SB(1, 1), b3 + hstep, voffB); PG8_STAGE(PG8_SA(1, 0), a3, voffA);
;             PG8_WAIT_V(8); PG8_WAIT_L(0); PG8_BAR; PG8_MMA(1, 0, At, B0); PG8_MMA(1, 1, At, B1); PG8_BAR; PG8_SCHED;
;     ...
;         if constexpr (ALIGN_EPI) { if (wr == 0) PG8_BAR; }
	s_add_i32 s3, s3, s1
	v_lshl_add_u64 v[240:241], v[244:245], 0, s[70:71]
	s_mov_b32 m0, s3
	ds_read_b128 v[208:211], v175 offset:49152
	ds_read_b128 v[212:215], v175 offset:50176
	ds_read_b128 v[216:219], v175 offset:51200
	ds_read_b128 v[220:223], v175 offset:52224
	ds_read_b128 v[224:227], v175 offset:53248
	ds_read_b128 v[228:231], v175 offset:54272
	ds_read_b128 v[232:235], v175 offset:55296
	ds_read_b128 v[236:239], v175 offset:56320
	global_load_lds_dwordx4 v[240:241], off
	v_lshl_add_u64 v[240:241], v[246:247], 0, s[70:71]
	s_add_i32 m0, s3, 0x2000
	s_add_i32 s3, s13, s1
	global_load_lds_dwordx4 v[240:241], off
	v_lshl_add_u64 v[240:241], v[242:243], 0, s[86:87]
	v_lshl_add_u64 v[242:243], v[240:241], 0, v[128:129]
	s_mov_b32 m0, s3
	v_lshl_add_u64 v[240:241], v[240:241], 0, v[144:145]
	global_load_lds_dwordx4 v[242:243], off
	s_add_i32 m0, s3, 0x2000
	s_nop 0
	global_load_lds_dwordx4 v[240:241], off
	v_lshl_add_u64 v[240:241], v[248:249], 0, s[70:71]
	s_mov_b32 m0, s20
	s_nop 0
	global_load_lds_dwordx4 v[240:241], off
	v_lshl_add_u64 v[240:241], v[250:251], 0, s[70:71]
	s_mov_b32 m0, s21
	s_nop 0
	global_load_lds_dwordx4 v[240:241], off
	s_waitcnt vmcnt(8) lgkmcnt(0)
	s_barrier
	v_mfma_f32_16x16x32_bf16 v[60:63], v[176:179], v[208:211], v[60:63]
	v_mfma_f32_16x16x32_bf16 v[56:59], v[184:187], v[208:211], v[56:59]
	v_mfma_f32_16x16x32_bf16 v[52:55], v[176:179], v[216:219], v[52:55]
	v_mfma_f32_16x16x32_bf16 v[44:47], v[184:187], v[216:219], v[44:47]
	v_mfma_f32_16x16x32_bf16 v[36:39], v[176:179], v[224:227], v[36:39]
	v_mfma_f32_16x16x32_bf16 v[28:31], v[184:187], v[224:227], v[28:31]
	v_mfma_f32_16x16x32_bf16 v[20:23], v[176:179], v[232:235], v[20:23]
	v_mfma_f32_16x16x32_bf16 v[12:15], v[184:187], v[232:235], v[12:15]
	v_mfma_f32_16x16x32_bf16 v[60:63], v[180:183], v[212:215], v[60:63]
	v_mfma_f32_16x16x32_bf16 v[56:59], v[188:191], v[212:215], v[56:59]
	v_mfma_f32_16x16x32_bf16 v[52:55], v[180:183], v[220:223], v[52:55]
	v_mfma_f32_16x16x32_bf16 v[44:47], v[188:191], v[220:223], v[44:47]
	v_mfma_f32_16x16x32_bf16 v[36:39], v[180:183], v[228:231], v[36:39]
	v_mfma_f32_16x16x32_bf16 v[28:31], v[188:191], v[228:231], v[28:31]
	v_mfma_f32_16x16x32_bf16 v[20:23], v[180:183], v[236:239], v[20:23]
	v_mfma_f32_16x16x32_bf16 v[12:15], v[188:191], v[236:239], v[12:15]
	v_mfma_f32_16x16x32_bf16 v[48:51], v[192:195], v[208:211], v[48:51]
	v_mfma_f32_16x16x32_bf16 v[40:43], v[200:203], v[208:211], v[40:43]
	v_mfma_f32_16x16x32_bf16 v[32:35], v[192:195], v[216:219], v[32:35]
	v_mfma_f32_16x16x32_bf16 v[24:27], v[200:203], v[216:219], v[24:27]
	v_mfma_f32_16x16x32_bf16 v[16:19], v[192:195], v[224:227], v[16:19]
	v_mfma_f32_16x16x32_bf16 v[8:11], v[200:203], v[224:227], v[8:11]
	v_mfma_f32_16x16x32_bf16 v[4:7], v[192:195], v[232:235], v[4:7]
	v_mfma_f32_16x16x32_bf16 v[0:3], v[200:203], v[232:235], v[0:3]
	v_mfma_f32_16x16x32_bf16 v[48:51], v[196:199], v[212:215], v[48:51]
	v_mfma_f32_16x16x32_bf16 v[40:43], v[204:207], v[212:215], v[40:43]
	v_mfma_f32_16x16x32_bf16 v[32:35], v[196:199], v[220:223], v[32:35]
	v_mfma_f32_16x16x32_bf16 v[24:27], v[204:207], v[220:223], v[24:27]
	v_mfma_f32_16x16x32_bf16 v[16:19], v[196:199], v[228:231], v[16:19]
	v_mfma_f32_16x16x32_bf16 v[8:11], v[204:207], v[228:231], v[8:11]
	v_mfma_f32_16x16x32_bf16 v[4:7], v[196:199], v[236:239], v[4:7]
	v_mfma_f32_16x16x32_bf16 v[0:3], v[204:207], v[236:239], v[0:3]
	s_barrier
	s_add_i32 s2, s2, 2
	v_lshl_add_u64 v[164:165], v[164:165], 0, s[82:83]
	s_cmp_gt_u32 s2, 29
	v_lshl_add_u64 v[166:167], v[166:167], 0, s[82:83]
	s_cbranch_scc0 .LBB0_405
	s_and_b64 vcc, exec, s[10:11]
	s_cbranch_vccz .LBB0_408
	s_barrier

; #define PG8_STAGE(bufoff, gbase, voff) do { _Pragma("unroll") for (int _i = 0; _i < 2; ++_i) \
;         __builtin_amdgcn_global_load_lds((const unsigned*)((const char*)(gbase) + (voff)[_i]), (PG8_LAS unsigned*)(lds + (bufoff) + ldsw + _i * 8192), 16, 0, 0); } while (0)
; #define PG8_LDA(dst, b, h) do { _Pragma("unroll") for (int m = 0; m < 4; ++m) _Pragma("unroll") for (int k = 0; k < 2; ++k) dst[m][k] = *(const PG8_LAS bf16x8*)(lds + PG8_SA(b, h) + aoff + m * 2048 + k * 1024); } while (0)
; #define PG8_LDB(dst, b, h) do { _Pragma("unroll") for (int n = 0; n < 2; ++n) _Pragma("unroll") for (int k = 0; k < 2; ++k) dst[n][k] = *(const PG8_LAS bf16x8*)(lds + PG8_SB(b, h) + boff + n * 2048 + k * 1024); } while (0)
; #define PG8_MMA(ai, bj, At, Bt) do { __builtin_amdgcn_s_setprio(1); _Pragma("unroll") for (int m = 0; m < 4; ++m) _Pragma("unroll") for (int n = 0; n < 2; ++n) _Pragma("unroll") for (int k = 0; k < 2; ++k) \
;         acc[ai][bj][m][n] = __builtin_amdgcn_mfma_f32_16x16x32_bf16(Bt[n][k], At[m][k], acc[ai][bj][m][n], 0, 0, 0); __builtin_amdgcn_s_setprio(0); } while (0)
; #define PG8_WAIT_V(n) asm volatile("s_waitcnt vmcnt(" #n ")" ::: "memory")
; #define PG8_WAIT_L(n) asm volatile("s_waitcnt lgkmcnt(" #n ")" ::: "memory")
; #define PG8_BAR __builtin_amdgcn_s_barrier()
; #define PG8_SCHED __builtin_amdgcn_sched_barrier(0)
; template <class Epi, class Sched, bool ALIGN_EPI = false, bool SP2 = false>
; __device__ __forceinline__ void gemm_phase(PG8_LAS unsigned char* lds, const Gemm g, const Sched& S, const Epi& E, int tid_in) {
;     ...
;             const bool last = (t == nt - 2);
;             const char* a1 = cA + (size_t)(t + 1) * kstep;
;             const char* a2 = last ? nA : cA + (size_t)(t + 2) * kstep; const char* b2 = last ? nB : cB + (size_t)(t + 2) * kstep;
;             const char* a3 = a2 + kstep; const char* b3 = b2 + kstep;
;             if (last && has_next) S.a_ready(nxt);
;             if constexpr (SP2) {
;             PG8_LDB(B0, 0, 0); PG8_LDB(B1, 0, 1); PG8_SCHED; PG8_LDA(At, 0, 0); PG8_STAGE(PG8_SA(1, 1), a1 + hstep, voffA);
;             PG8_WAIT_V(8); PG8_WAIT_L(0); PG8_BAR; PG8_MMA(0, 0, At, B0); PG8_MMA(0, 1, At, B1); PG8_BAR; PG8_SCHED;
;             PG8_LDA(At, 0, 1); PG8_STAGE(PG8_SB(0, 0), b2, voffB); PG8_STAGE(PG8_SB(0, 1), b2 + hstep, voffB); PG8_STAGE(PG8_SA(0, 0), a2, voffA);
.LBB0_588:
	s_cmp_eq_u32 s2, 28
	s_cselect_b64 vcc, -1, 0
	s_add_i32 s3, 0, 0x10000
	s_add_i32 s11, 0, 0x14000
	v_lshl_add_u64 v[176:177], v[166:167], 0, s[52:53]
	v_add_u32_e32 v188, s3, v168
	v_add_u32_e32 v204, s11, v168
	v_cndmask_b32_e32 v241, v177, v131, vcc
	v_cndmask_b32_e32 v240, v176, v160, vcc
	ds_read_b128 v[176:179], v188
	ds_read_b128 v[180:183], v188 offset:1024
	ds_read_b128 v[184:187], v188 offset:2048
	ds_read_b128 v[188:191], v188 offset:3072
	ds_read_b128 v[192:195], v204
	ds_read_b128 v[196:199], v204 offset:1024
	ds_read_b128 v[200:203], v204 offset:2048
	ds_read_b128 v[204:207], v204 offset:3072
	v_cndmask_b32_e32 v243, v165, v161, vcc
	v_cndmask_b32_e32 v242, v164, v162, vcc
	v_lshl_add_u64 v[244:245], v[166:167], 0, v[154:155]
	s_add_i32 m0, s15, 0xc000
	ds_read_b128 v[208:211], v175
	ds_read_b128 v[212:215], v175 offset:1024
	ds_read_b128 v[216:219], v175 offset:2048
	ds_read_b128 v[220:223], v175 offset:3072
	ds_read_b128 v[224:227], v175 offset:4096
	ds_read_b128 v[228:231], v175 offset:5120
	ds_read_b128 v[232:235], v175 offset:6144
	ds_read_b128 v[236:239], v175 offset:7168
	global_load_lds_dwordx4 v[244:245], off
	v_lshl_add_u64 v[244:245], v[166:167], 0, v[152:153]
	s_add_i32 m0, s15, 0xe000
	s_nop 0
	global_load_lds_dwordx4 v[244:245], off
	s_waitcnt vmcnt(8) lgkmcnt(0)
	s_barrier
	v_mfma_f32_16x16x32_bf16 v[124:127], v[176:179], v[208:211], v[124:127]
	v_mfma_f32_16x16x32_bf16 v[116:119], v[184:187], v[208:211], v[116:119]
	v_mfma_f32_16x16x32_bf16 v[108:111], v[176:179], v[216:219], v[108:111]
	v_mfma_f32_16x16x32_bf16 v[100:103], v[184:187], v[216:219], v[100:103]
	v_mfma_f32_16x16x32_bf16 v[92:95], v[176:179], v[224:227], v[92:95]
	v_mfma_f32_16x16x32_bf16 v[84:87], v[184:187], v[224:227], v[84:87]
	v_mfma_f32_16x16x32_bf16 v[76:79], v[176:179], v[232:235], v[76:79]
	v_mfma_f32_16x16x32_bf16 v[68:71], v[184:187], v[232:235], v[68:71]
	v_mfma_f32_16x16x32_bf16 v[124:127], v[180:183], v[212:215], v[124:127]
	v_mfma_f32_16x16x32_bf16 v[116:119], v[188:191], v[212:215], v[116:119]
	v_mfma_f32_16x16x32_bf16 v[108:111], v[180:183], v[220:223], v[108:111]
	v_mfma_f32_16x16x32_bf16 v[100:103], v[188:191], v[220:223], v[100:103]
	v_mfma_f32_16x16x32_bf16 v[92:95], v[180:183], v[228:231], v[92:95]
	v_mfma_f32_16x16x32_bf16 v[84:87], v[188:191], v[228:231], v[84:87]
	v_mfma_f32_16x16x32_bf16 v[76:79], v[180:183], v[236:239], v[76:79]
	v_mfma_f32_16x16x32_bf16 v[68:71], v[188:191], v[236:239], v[68:71]
	v_mfma_f32_16x16x32_bf16 v[120:123], v[192:195], v[208:211], v[120:123]
	v_mfma_f32_16x16x32_bf16 v[112:115], v[200:203], v[208:211], v[112:115]
	v_mfma_f32_16x16x32_bf16 v[104:107], v[192:195], v[216:219], v[104:107]
	v_mfma_f32_16x16x32_bf16 v[96:99], v[200:203], v[216:219], v[96:99]
	v_mfma_f32_16x16x32_bf16 v[88:91], v[192:195], v[224:227], v[88:91]
	v_mfma_f32_16x16x32_bf16 v[80:83], v[200:203], v[224:227], v[80:83]
	v_mfma_f32_16x16x32_bf16 v[72:75], v[192:195], v[232:235], v[72:75]
	v_mfma_f32_16x16x32_bf16 v[64:67], v[200:203], v[232:235], v[64:67]
	v_mfma_f32_16x16x32_bf16 v[120:123], v[196:199], v[212:215], v[120:123]
	v_mfma_f32_16x16x32_bf16 v[112:115], v[204:207], v[212:215], v[112:115]
	v_mfma_f32_16x16x32_bf16 v[104:107], v[196:199], v[220:223], v[104:107]
	v_mfma_f32_16x16x32_bf16 v[96:99], v[204:207], v[220:223], v[96:99]
	v_mfma_f32_16x16x32_bf16 v[88:91], v[196:199], v[228:231], v[88:91]
	v_mfma_f32_16x16x32_bf16 v[80:83], v[204:207], v[228:231], v[80:83]
	v_mfma_f32_16x16x32_bf16 v[72:75], v[196:199], v[236:239], v[72:75]
	v_mfma_f32_16x16x32_bf16 v[64:67], v[204:207], v[236:239], v[64:67]
	s_barrier
	s_add_i32 s3, s3, s14
	v_lshl_add_u64 v[244:245], v[242:243], 0, v[128:129]
	s_mov_b32 m0, s3
	ds_read_b128 v[208:211], v175 offset:16384
	ds_read_b128 v[212:215], v175 offset:17408
	ds_read_b128 v[216:219], v175 offset:18432
	ds_read_b128 v[220:223], v175 offset:19456
	ds_read_b128 v[224:227], v175 offset:20480
	ds_read_b128 v[228:231], v175 offset:21504
	ds_read_b128 v[232:235], v175 offset:22528
	ds_read_b128 v[236:239], v175 offset:23552
	global_load_lds_dwordx4 v[244:245], off
	v_lshl_add_u64 v[246:247], v[242:243], 0, v[144:145]
	s_add_i32 m0, s3, 0x2000
	v_lshl_add_u64 v[248:249], v[242:243], 0, s[98:99]
	s_add_i32 s3, s11, s14
	global_load_lds_dwordx4 v[246:247], off
	v_lshl_add_u64 v[250:251], v[248:249], 0, v[128:129]
	s_mov_b32 m0, s3
	v_lshl_add_u64 v[248:249], v[248:249], 0, v[144:145]
	global_load_lds_dwordx4 v[250:251], off
	s_add_i32 m0, s3, 0x2000
	v_lshl_add_u64 v[250:251], v[240:241], 0, v[146:147]
	global_load_lds_dwordx4 v[248:249], off
	v_lshl_add_u64 v[248:249], v[240:241], 0, v[148:149]
	s_mov_b32 m0, s15
	s_nop 0
	global_load_lds_dwordx4 v[248:249], off
	s_mov_b32 m0, s16
	s_nop 0
	global_load_lds_dwordx4 v[250:251], off
	s_waitcnt vmcnt(8) lgkmcnt(0)
	s_barrier
; #define PG8_STAGE(bufoff, gbase, voff) do { _Pragma("unroll") for (int _i = 0; _i < 2; ++_i) \
;         __builtin_amdgcn_global_load_lds((const unsigned*)((const char*)(gbase) + (voff)[_i]), (PG8_LAS unsigned*)(lds + (bufoff) + ldsw + _i * 8192), 16, 0, 0); } while (0)
; #define PG8_LDA(dst, b, h) do { _Pragma("unroll") for (int m = 0; m < 4; ++m) _Pragma("unroll") for (int k = 0; k < 2; ++k) dst[m][k] = *(const PG8_LAS bf16x8*)(lds + PG8_SA(b, h) + aoff + m * 2048 + k * 1024); } while (0)
; #define PG8_LDB(dst, b, h) do { _Pragma("unroll") for (int n = 0; n < 2; ++n) _Pragma("unroll") for (int k = 0; k < 2; ++k) dst[n][k] = *(const PG8_LAS bf16x8*)(lds + PG8_SB(b, h) + boff + n * 2048 + k * 1024); } while (0)
; #define PG8_MMA(ai, bj, At, Bt) do { __builtin_amdgcn_s_setprio(1); _Pragma("unroll") for (int m = 0; m < 4; ++m) _Pragma("unroll") for (int n = 0; n < 2; ++n) _Pragma("unroll") for (int k = 0; k < 2; ++k) \
;         acc[ai][bj][m][n] = __builtin_amdgcn_mfma_f32_16x16x32_bf16(Bt[n][k], At[m][k], acc[ai][bj][m][n], 0, 0, 0); __builtin_amdgcn_s_setprio(0); } while (0)
; #define PG8_WAIT_V(n) asm volatile("s_waitcnt vmcnt(" #n ")" ::: "memory")
; #define PG8_WAIT_L(n) asm volatile("s_waitcnt lgkmcnt(" #n ")" ::: "memory")
; #define PG8_BAR __builtin_amdgcn_s_barrier()
; #define PG8_SCHED __builtin_amdgcn_sched_barrier(0)
; template <class Epi, class Sched, bool ALIGN_EPI = false, bool SP2 = false>
; __device__ __forceinline__ void gemm_phase(PG8_LAS unsigned char* lds, const Gemm g, const Sched& S, const Epi& E, int tid_in) {
;     ...
;             PG8_WAIT_V(8); PG8_WAIT_L(0); PG8_BAR; PG8_MMA(1, 0, At, B0); PG8_MMA(1, 1, At, B1); PG8_BAR; PG8_SCHED;
;             PG8_LDB(B0, 1, 0); PG8_LDB(B1, 1, 1); PG8_SCHED; PG8_LDA(At, 1, 0); PG8_STAGE(PG8_SA(0, 1), a2 + hstep, voffA);
;             PG8_WAIT_V(8); PG8_WAIT_L(0); PG8_BAR; PG8_MMA(0, 0, At, B0); PG8_MMA(0, 1, At, B1); PG8_BAR; PG8_SCHED;
	v_mfma_f32_16x16x32_bf16 v[60:63], v[176:179], v[208:211], v[60:63]
	v_mfma_f32_16x16x32_bf16 v[52:55], v[184:187], v[208:211], v[52:55]
	v_mfma_f32_16x16x32_bf16 v[44:47], v[176:179], v[216:219], v[44:47]
	v_mfma_f32_16x16x32_bf16 v[36:39], v[184:187], v[216:219], v[36:39]
	v_mfma_f32_16x16x32_bf16 v[28:31], v[176:179], v[224:227], v[28:31]
	v_mfma_f32_16x16x32_bf16 v[20:23], v[184:187], v[224:227], v[20:23]
	v_mfma_f32_16x16x32_bf16 v[12:15], v[176:179], v[232:235], v[12:15]
	v_mfma_f32_16x16x32_bf16 v[4:7], v[184:187], v[232:235], v[4:7]
	v_mfma_f32_16x16x32_bf16 v[60:63], v[180:183], v[212:215], v[60:63]
	v_mfma_f32_16x16x32_bf16 v[52:55], v[188:191], v[212:215], v[52:55]
	v_mfma_f32_16x16x32_bf16 v[44:47], v[180:183], v[220:223], v[44:47]
	v_mfma_f32_16x16x32_bf16 v[36:39], v[188:191], v[220:223], v[36:39]
	v_mfma_f32_16x16x32_bf16 v[28:31], v[180:183], v[228:231], v[28:31]
	v_mfma_f32_16x16x32_bf16 v[20:23], v[188:191], v[228:231], v[20:23]
	v_mfma_f32_16x16x32_bf16 v[12:15], v[180:183], v[236:239], v[12:15]
	v_mfma_f32_16x16x32_bf16 v[4:7], v[188:191], v[236:239], v[4:7]
	v_mfma_f32_16x16x32_bf16 v[56:59], v[192:195], v[208:211], v[56:59]
	v_mfma_f32_16x16x32_bf16 v[48:51], v[200:203], v[208:211], v[48:51]
	v_mfma_f32_16x16x32_bf16 v[40:43], v[192:195], v[216:219], v[40:43]
	v_mfma_f32_16x16x32_bf16 v[32:35], v[200:203], v[216:219], v[32:35]
	v_mfma_f32_16x16x32_bf16 v[24:27], v[192:195], v[224:227], v[24:27]
	v_mfma_f32_16x16x32_bf16 v[16:19], v[200:203], v[224:227], v[16:19]
	v_mfma_f32_16x16x32_bf16 v[8:11], v[192:195], v[232:235], v[8:11]
	v_mfma_f32_16x16x32_bf16 v[0:3], v[200:203], v[232:235], v[0:3]
	v_mfma_f32_16x16x32_bf16 v[56:59], v[196:199], v[212:215], v[56:59]
	v_mfma_f32_16x16x32_bf16 v[48:51], v[204:207], v[212:215], v[48:51]
	v_mfma_f32_16x16x32_bf16 v[40:43], v[196:199], v[220:223], v[40:43]
	v_mfma_f32_16x16x32_bf16 v[32:35], v[204:207], v[220:223], v[32:35]
	v_mfma_f32_16x16x32_bf16 v[24:27], v[196:199], v[228:231], v[24:27]
	v_mfma_f32_16x16x32_bf16 v[16:19], v[204:207], v[228:231], v[16:19]
	v_mfma_f32_16x16x32_bf16 v[8:11], v[196:199], v[236:239], v[8:11]
	v_mfma_f32_16x16x32_bf16 v[0:3], v[204:207], v[236:239], v[0:3]
	s_barrier
	s_add_i32 s3, 0, 0x18000
	s_add_i32 s11, 0, 0x1c000
	v_add_u32_e32 v188, s3, v168
	v_add_u32_e32 v204, s11, v168
	ds_read_b128 v[176:179], v188
	ds_read_b128 v[180:183], v188 offset:1024
	ds_read_b128 v[184:187], v188 offset:2048
	ds_read_b128 v[188:191], v188 offset:3072
	ds_read_b128 v[192:195], v204
	ds_read_b128 v[196:199], v204 offset:1024
	ds_read_b128 v[200:203], v204 offset:2048
	ds_read_b128 v[204:207], v204 offset:3072
	v_lshl_add_u64 v[240:241], v[240:241], 0, s[98:99]
	s_mov_b32 m0, s17
	v_lshl_add_u64 v[252:253], v[240:241], 0, v[148:149]
	ds_read_b128 v[208:211], v175 offset:32768
	ds_read_b128 v[212:215], v175 offset:33792
	ds_read_b128 v[216:219], v175 offset:34816
	ds_read_b128 v[220:223], v175 offset:35840
	ds_read_b128 v[224:227], v175 offset:36864
	ds_read_b128 v[228:231], v175 offset:37888
	ds_read_b128 v[232:235], v175 offset:38912
	ds_read_b128 v[236:239], v175 offset:39936
	global_load_lds_dwordx4 v[252:253], off
	v_lshl_add_u64 v[240:241], v[240:241], 0, v[146:147]
	s_mov_b32 m0, s18
	s_nop 0
	global_load_lds_dwordx4 v[240:241], off
	s_waitcnt vmcnt(8) lgkmcnt(0)
	s_barrier
	v_mfma_f32_16x16x32_bf16 v[124:127], v[176:179], v[208:211], v[124:127]
	v_mfma_f32_16x16x32_bf16 v[116:119], v[184:187], v[208:211], v[116:119]
	v_mfma_f32_16x16x32_bf16 v[108:111], v[176:179], v[216:219], v[108:111]
	v_mfma_f32_16x16x32_bf16 v[100:103], v[184:187], v[216:219], v[100:103]
	v_mfma_f32_16x16x32_bf16 v[92:95], v[176:179], v[224:227], v[92:95]
	v_mfma_f32_16x16x32_bf16 v[84:87], v[184:187], v[224:227], v[84:87]
	v_mfma_f32_16x16x32_bf16 v[76:79], v[176:179], v[232:235], v[76:79]
	v_mfma_f32_16x16x32_bf16 v[68:71], v[184:187], v[232:235], v[68:71]
	v_mfma_f32_16x16x32_bf16 v[124:127], v[180:183], v[212:215], v[124:127]
	v_mfma_f32_16x16x32_bf16 v[116:119], v[188:191], v[212:215], v[116:119]
	v_mfma_f32_16x16x32_bf16 v[108:111], v[180:183], v[220:223], v[108:111]
	v_mfma_f32_16x16x32_bf16 v[100:103], v[188:191], v[220:223], v[100:103]
	v_mfma_f32_16x16x32_bf16 v[92:95], v[180:183], v[228:231], v[92:95]
	v_mfma_f32_16x16x32_bf16 v[84:87], v[188:191], v[228:231], v[84:87]
	v_mfma_f32_16x16x32_bf16 v[76:79], v[180:183], v[236:239], v[76:79]
	v_mfma_f32_16x16x32_bf16 v[68:71], v[188:191], v[236:239], v[68:71]
	v_mfma_f32_16x16x32_bf16 v[120:123], v[192:195], v[208:211], v[120:123]
	v_mfma_f32_16x16x32_bf16 v[112:115], v[200:203], v[208:211], v[112:115]
	v_mfma_f32_16x16x32_bf16 v[104:107], v[192:195], v[216:219], v[104:107]
	v_mfma_f32_16x16x32_bf16 v[96:99], v[200:203], v[216:219], v[96:99]
	v_mfma_f32_16x16x32_bf16 v[88:91], v[192:195], v[224:227], v[88:91]
	v_mfma_f32_16x16x32_bf16 v[80:83], v[200:203], v[224:227], v[80:83]
	v_mfma_f32_16x16x32_bf16 v[72:75], v[192:195], v[232:235], v[72:75]
	v_mfma_f32_16x16x32_bf16 v[64:67], v[200:203], v[232:235], v[64:67]
	v_mfma_f32_16x16x32_bf16 v[120:123], v[196:199], v[212:215], v[120:123]
	v_mfma_f32_16x16x32_bf16 v[112:115], v[204:207], v[212:215], v[112:115]
	v_mfma_f32_16x16x32_bf16 v[104:107], v[196:199], v[220:223], v[104:107]
	v_mfma_f32_16x16x32_bf16 v[96:99], v[204:207], v[220:223], v[96:99]
	v_mfma_f32_16x16x32_bf16 v[88:91], v[196:199], v[228:231], v[88:91]
	v_mfma_f32_16x16x32_bf16 v[80:83], v[204:207], v[228:231], v[80:83]
	v_mfma_f32_16x16x32_bf16 v[72:75], v[196:199], v[236:239], v[72:75]
	v_mfma_f32_16x16x32_bf16 v[64:67], v[204:207], v[236:239], v[64:67]
	s_barrier
; #define PG8_STAGE(bufoff, gbase, voff) do { _Pragma("unroll") for (int _i = 0; _i < 2; ++_i) \
;         __builtin_amdgcn_global_load_lds((const unsigned*)((const char*)(gbase) + (voff)[_i]), (PG8_LAS unsigned*)(lds + (bufoff) + ldsw + _i * 8192), 16, 0, 0); } while (0)
; #define PG8_LDA(dst, b, h) do { _Pragma("unroll") for (int m = 0; m < 4; ++m) _Pragma("unroll") for (int k = 0; k < 2; ++k) dst[m][k] = *(const PG8_LAS bf16x8*)(lds + PG8_SA(b, h) + aoff + m * 2048 + k * 1024); } while (0)
; #define PG8_MMA(ai, bj, At, Bt) do { __builtin_amdgcn_s_setprio(1); _Pragma("unroll") for (int m = 0; m < 4; ++m) _Pragma("unroll") for (int n = 0; n < 2; ++n) _Pragma("unroll") for (int k = 0; k < 2; ++k) \
;         acc[ai][bj][m][n] = __builtin_amdgcn_mfma_f32_16x16x32_bf16(Bt[n][k], At[m][k], acc[ai][bj][m][n], 0, 0, 0); __builtin_amdgcn_s_setprio(0); } while (0)
; #define PG8_WAIT_V(n) asm volatile("s_waitcnt vmcnt(" #n ")" ::: "memory")
; #define PG8_WAIT_L(n) asm volatile("s_waitcnt lgkmcnt(" #n ")" ::: "memory")
; #define PG8_BAR __builtin_amdgcn_s_barrier()
; #define PG8_SCHED __builtin_amdgcn_sched_barrier(0)
; template <class Epi, class Sched, bool ALIGN_EPI = false, bool SP2 = false>
; __device__ __forceinline__ void gemm_phase(PG8_LAS unsigned char* lds, const Gemm g, const Sched& S, const Epi& E, int tid_in) {
;     ...
;         for (int t = 0; t < nt; t += 2) {
;             const bool last = (t == nt - 2);
;             const char* a1 = cA + (size_t)(t + 1) * kstep;
;             const char* a2 = last ? nA : cA + (size_t)(t + 2) * kstep; const char* b2 = last ? nB : cB + (size_t)(t + 2) * kstep;
;             const char* a3 = a2 + kstep; const char* b3 = b2 + kstep;
;     ...
;             PG8_LDA(At, 1, 1); PG8_STAGE(PG8_SB(1, 0), b3, voffB); PG8_STAGE(PG8_SB(1, 1), b3 + hstep, voffB); PG8_STAGE(PG8_SA(1, 0), a3, voffA);
;             PG8_WAIT_V(8); PG8_WAIT_L(0); PG8_BAR; PG8_MMA(1, 0, At, B0); PG8_MMA(1, 1, At, B1); PG8_BAR; PG8_SCHED;
;     ...
;         if constexpr (ALIGN_EPI) { if (wr == 0) PG8_BAR; }
	s_add_i32 s3, s3, s14
	v_lshl_add_u64 v[240:241], v[244:245], 0, s[70:71]
	s_mov_b32 m0, s3
	ds_read_b128 v[208:211], v175 offset:49152
	ds_read_b128 v[212:215], v175 offset:50176
	ds_read_b128 v[216:219], v175 offset:51200
	ds_read_b128 v[220:223], v175 offset:52224
	ds_read_b128 v[224:227], v175 offset:53248
	ds_read_b128 v[228:231], v175 offset:54272
	ds_read_b128 v[232:235], v175 offset:55296
	ds_read_b128 v[236:239], v175 offset:56320
	global_load_lds_dwordx4 v[240:241], off
	v_lshl_add_u64 v[240:241], v[246:247], 0, s[70:71]
	s_add_i32 m0, s3, 0x2000
	s_add_i32 s3, s11, s14
	global_load_lds_dwordx4 v[240:241], off
	v_lshl_add_u64 v[240:241], v[242:243], 0, s[86:87]
	v_lshl_add_u64 v[242:243], v[240:241], 0, v[128:129]
	s_mov_b32 m0, s3
	v_lshl_add_u64 v[240:241], v[240:241], 0, v[144:145]
	global_load_lds_dwordx4 v[242:243], off
	s_add_i32 m0, s3, 0x2000
	s_nop 0
	global_load_lds_dwordx4 v[240:241], off
	v_lshl_add_u64 v[240:241], v[248:249], 0, s[70:71]
	s_mov_b32 m0, s19
	s_nop 0
	global_load_lds_dwordx4 v[240:241], off
	v_lshl_add_u64 v[240:241], v[250:251], 0, s[70:71]
	s_mov_b32 m0, s1
	s_nop 0
	global_load_lds_dwordx4 v[240:241], off
	s_waitcnt vmcnt(8) lgkmcnt(0)
	s_barrier
	v_mfma_f32_16x16x32_bf16 v[60:63], v[176:179], v[208:211], v[60:63]
	v_mfma_f32_16x16x32_bf16 v[52:55], v[184:187], v[208:211], v[52:55]
	v_mfma_f32_16x16x32_bf16 v[44:47], v[176:179], v[216:219], v[44:47]
	v_mfma_f32_16x16x32_bf16 v[36:39], v[184:187], v[216:219], v[36:39]
	v_mfma_f32_16x16x32_bf16 v[28:31], v[176:179], v[224:227], v[28:31]
	v_mfma_f32_16x16x32_bf16 v[20:23], v[184:187], v[224:227], v[20:23]
	v_mfma_f32_16x16x32_bf16 v[12:15], v[176:179], v[232:235], v[12:15]
	v_mfma_f32_16x16x32_bf16 v[4:7], v[184:187], v[232:235], v[4:7]
	v_mfma_f32_16x16x32_bf16 v[60:63], v[180:183], v[212:215], v[60:63]
	v_mfma_f32_16x16x32_bf16 v[52:55], v[188:191], v[212:215], v[52:55]
	v_mfma_f32_16x16x32_bf16 v[44:47], v[180:183], v[220:223], v[44:47]
	v_mfma_f32_16x16x32_bf16 v[36:39], v[188:191], v[220:223], v[36:39]
	v_mfma_f32_16x16x32_bf16 v[28:31], v[180:183], v[228:231], v[28:31]
	v_mfma_f32_16x16x32_bf16 v[20:23], v[188:191], v[228:231], v[20:23]
	v_mfma_f32_16x16x32_bf16 v[12:15], v[180:183], v[236:239], v[12:15]
	v_mfma_f32_16x16x32_bf16 v[4:7], v[188:191], v[236:239], v[4:7]
	v_mfma_f32_16x16x32_bf16 v[56:59], v[192:195], v[208:211], v[56:59]
	v_mfma_f32_16x16x32_bf16 v[48:51], v[200:203], v[208:211], v[48:51]
	v_mfma_f32_16x16x32_bf16 v[40:43], v[192:195], v[216:219], v[40:43]
	v_mfma_f32_16x16x32_bf16 v[32:35], v[200:203], v[216:219], v[32:35]
	v_mfma_f32_16x16x32_bf16 v[24:27], v[192:195], v[224:227], v[24:27]
	v_mfma_f32_16x16x32_bf16 v[16:19], v[200:203], v[224:227], v[16:19]
	v_mfma_f32_16x16x32_bf16 v[8:11], v[192:195], v[232:235], v[8:11]
	v_mfma_f32_16x16x32_bf16 v[0:3], v[200:203], v[232:235], v[0:3]
	v_mfma_f32_16x16x32_bf16 v[56:59], v[196:199], v[212:215], v[56:59]
	v_mfma_f32_16x16x32_bf16 v[48:51], v[204:207], v[212:215], v[48:51]
	v_mfma_f32_16x16x32_bf16 v[40:43], v[196:199], v[220:223], v[40:43]
	v_mfma_f32_16x16x32_bf16 v[32:35], v[204:207], v[220:223], v[32:35]
	v_mfma_f32_16x16x32_bf16 v[24:27], v[196:199], v[228:231], v[24:27]
	v_mfma_f32_16x16x32_bf16 v[16:19], v[204:207], v[228:231], v[16:19]
	v_mfma_f32_16x16x32_bf16 v[8:11], v[196:199], v[236:239], v[8:11]
	v_mfma_f32_16x16x32_bf16 v[0:3], v[204:207], v[236:239], v[0:3]
	s_barrier
	s_add_i32 s2, s2, 2
	v_lshl_add_u64 v[164:165], v[164:165], 0, s[82:83]
	s_cmp_gt_u32 s2, 29
	v_lshl_add_u64 v[166:167], v[166:167], 0, s[82:83]
	s_cbranch_scc0 .LBB0_588
	s_and_b64 vcc, exec, s[8:9]
	s_cbranch_vccz .LBB0_591
	s_barrier

; #define PG8_STAGE(bufoff, gbase, voff) do { _Pragma("unroll") for (int _i = 0; _i < 2; ++_i) \
;         __builtin_amdgcn_global_load_lds((const unsigned*)((const char*)(gbase) + (voff)[_i]), (PG8_LAS unsigned*)(lds + (bufoff) + ldsw + _i * 8192), 16, 0, 0); } while (0)
; #define PG8_LDA(dst, b, h) do { _Pragma("unroll") for (int m = 0; m < 4; ++m) _Pragma("unroll") for (int k = 0; k < 2; ++k) dst[m][k] = *(const PG8_LAS bf16x8*)(lds + PG8_SA(b, h) + aoff + m * 2048 + k * 1024); } while (0)
; #define PG8_LDB(dst, b, h) do { _Pragma("unroll") for (int n = 0; n < 2; ++n) _Pragma("unroll") for (int k = 0; k < 2; ++k) dst[n][k] = *(const PG8_LAS bf16x8*)(lds + PG8_SB(b, h) + boff + n * 2048 + k * 1024); } while (0)
; #define PG8_MMA(ai, bj, At, Bt) do { __builtin_amdgcn_s_setprio(1); _Pragma("unroll") for (int m = 0; m < 4; ++m) _Pragma("unroll") for (int n = 0; n < 2; ++n) _Pragma("unroll") for (int k = 0; k < 2; ++k) \
;         acc[ai][bj][m][n] = __builtin_amdgcn_mfma_f32_16x16x32_bf16(Bt[n][k], At[m][k], acc[ai][bj][m][n], 0, 0, 0); __builtin_amdgcn_s_setprio(0); } while (0)
; #define PG8_WAIT_V(n) asm volatile("s_waitcnt vmcnt(" #n ")" ::: "memory")
; #define PG8_WAIT_L(n) asm volatile("s_waitcnt lgkmcnt(" #n ")" ::: "memory")
; #define PG8_BAR __builtin_amdgcn_s_barrier()
; #define PG8_SCHED __builtin_amdgcn_sched_barrier(0)
; template <class Epi, class Sched, bool ALIGN_EPI = false, bool SP2 = false>
; __device__ __forceinline__ void gemm_phase(PG8_LAS unsigned char* lds, const Gemm g, const Sched& S, const Epi& E, int tid_in) {
;     ...
;             const bool last = (t == nt - 2);
;             const char* a1 = cA + (size_t)(t + 1) * kstep;
;             const char* a2 = last ? nA : cA + (size_t)(t + 2) * kstep; const char* b2 = last ? nB : cB + (size_t)(t + 2) * kstep;
;             const char* a3 = a2 + kstep; const char* b3 = b2 + kstep;
;             if (last && has_next) S.a_ready(nxt);
;             if constexpr (SP2) {
;             PG8_LDB(B0, 0, 0); PG8_LDB(B1, 0, 1); PG8_SCHED; PG8_LDA(At, 0, 0); PG8_STAGE(PG8_SA(1, 1), a1 + hstep, voffA);
;             PG8_WAIT_V(8); PG8_WAIT_L(0); PG8_BAR; PG8_MMA(0, 0, At, B0); PG8_MMA(0, 1, At, B1); PG8_BAR; PG8_SCHED;
;             PG8_LDA(At, 0, 1); PG8_STAGE(PG8_SB(0, 0), b2, voffB); PG8_STAGE(PG8_SB(0, 1), b2 + hstep, voffB); PG8_STAGE(PG8_SA(0, 0), a2, voffA);
.LBB0_683:
	s_cmpk_eq_i32 s2, 0x54
	s_cselect_b64 vcc, -1, 0
	s_add_i32 s3, 0, 0x10000
	v_add_u32_e32 v169, s3, v166
	s_add_i32 s8, 0, 0x14000
	ds_read_b128 v[176:179], v169
	ds_read_b128 v[180:183], v169 offset:1024
	ds_read_b128 v[184:187], v169 offset:2048
	ds_read_b128 v[188:191], v169 offset:3072
	v_add_u32_e32 v169, s8, v166
	ds_read_b128 v[192:195], v169
	ds_read_b128 v[196:199], v169 offset:1024
	ds_read_b128 v[200:203], v169 offset:2048
	ds_read_b128 v[204:207], v169 offset:3072
	v_lshl_add_u64 v[164:165], v[162:163], 0, s[82:83]
	v_cndmask_b32_e32 v241, v165, v157, vcc
	v_cndmask_b32_e32 v240, v164, v156, vcc
	v_cndmask_b32_e32 v243, v161, v159, vcc
	v_cndmask_b32_e32 v242, v160, v158, vcc
	v_lshl_add_u64 v[244:245], v[162:163], 0, v[154:155]
	s_add_i32 m0, s14, 0xc000
	ds_read_b128 v[208:211], v168
	ds_read_b128 v[212:215], v168 offset:1024
	ds_read_b128 v[216:219], v168 offset:2048
	ds_read_b128 v[220:223], v168 offset:3072
	ds_read_b128 v[224:227], v168 offset:4096
	ds_read_b128 v[228:231], v168 offset:5120
	ds_read_b128 v[232:235], v168 offset:6144
	ds_read_b128 v[236:239], v168 offset:7168
	global_load_lds_dwordx4 v[244:245], off
	v_lshl_add_u64 v[162:163], v[162:163], 0, v[152:153]
	s_add_i32 m0, s14, 0xe000
	s_nop 0
	global_load_lds_dwordx4 v[162:163], off
	s_waitcnt vmcnt(8) lgkmcnt(0)
	s_barrier
	v_mfma_f32_16x16x32_bf16 v[124:127], v[176:179], v[208:211], v[124:127]
	v_mfma_f32_16x16x32_bf16 v[120:123], v[184:187], v[208:211], v[120:123]
	v_mfma_f32_16x16x32_bf16 v[116:119], v[176:179], v[216:219], v[116:119]
	v_mfma_f32_16x16x32_bf16 v[108:111], v[184:187], v[216:219], v[108:111]
	v_mfma_f32_16x16x32_bf16 v[100:103], v[176:179], v[224:227], v[100:103]
	v_mfma_f32_16x16x32_bf16 v[92:95], v[184:187], v[224:227], v[92:95]
	v_mfma_f32_16x16x32_bf16 v[84:87], v[176:179], v[232:235], v[84:87]
	v_mfma_f32_16x16x32_bf16 v[76:79], v[184:187], v[232:235], v[76:79]
	v_mfma_f32_16x16x32_bf16 v[124:127], v[180:183], v[212:215], v[124:127]
	v_mfma_f32_16x16x32_bf16 v[120:123], v[188:191], v[212:215], v[120:123]
	v_mfma_f32_16x16x32_bf16 v[116:119], v[180:183], v[220:223], v[116:119]
	v_mfma_f32_16x16x32_bf16 v[108:111], v[188:191], v[220:223], v[108:111]
	v_mfma_f32_16x16x32_bf16 v[100:103], v[180:183], v[228:231], v[100:103]
	v_mfma_f32_16x16x32_bf16 v[92:95], v[188:191], v[228:231], v[92:95]
	v_mfma_f32_16x16x32_bf16 v[84:87], v[180:183], v[236:239], v[84:87]
	v_mfma_f32_16x16x32_bf16 v[76:79], v[188:191], v[236:239], v[76:79]
	v_mfma_f32_16x16x32_bf16 v[112:115], v[192:195], v[208:211], v[112:115]
	v_mfma_f32_16x16x32_bf16 v[104:107], v[200:203], v[208:211], v[104:107]
	v_mfma_f32_16x16x32_bf16 v[96:99], v[192:195], v[216:219], v[96:99]
	v_mfma_f32_16x16x32_bf16 v[88:91], v[200:203], v[216:219], v[88:91]
	v_mfma_f32_16x16x32_bf16 v[80:83], v[192:195], v[224:227], v[80:83]
	v_mfma_f32_16x16x32_bf16 v[72:75], v[200:203], v[224:227], v[72:75]
	v_mfma_f32_16x16x32_bf16 v[68:71], v[192:195], v[232:235], v[68:71]
	v_mfma_f32_16x16x32_bf16 v[64:67], v[200:203], v[232:235], v[64:67]
	v_mfma_f32_16x16x32_bf16 v[112:115], v[196:199], v[212:215], v[112:115]
	v_mfma_f32_16x16x32_bf16 v[104:107], v[204:207], v[212:215], v[104:107]
	v_mfma_f32_16x16x32_bf16 v[96:99], v[196:199], v[220:223], v[96:99]
	v_mfma_f32_16x16x32_bf16 v[88:91], v[204:207], v[220:223], v[88:91]
	v_mfma_f32_16x16x32_bf16 v[80:83], v[196:199], v[228:231], v[80:83]
	v_mfma_f32_16x16x32_bf16 v[72:75], v[204:207], v[228:231], v[72:75]
	v_mfma_f32_16x16x32_bf16 v[68:71], v[196:199], v[236:239], v[68:71]
	v_mfma_f32_16x16x32_bf16 v[64:67], v[204:207], v[236:239], v[64:67]
	s_barrier
	s_add_i32 s3, s3, s1
	v_lshl_add_u64 v[162:163], v[242:243], 0, v[128:129]
	s_mov_b32 m0, s3
	ds_read_b128 v[208:211], v168 offset:16384
	ds_read_b128 v[212:215], v168 offset:17408
	ds_read_b128 v[216:219], v168 offset:18432
	ds_read_b128 v[220:223], v168 offset:19456
	ds_read_b128 v[224:227], v168 offset:20480
	ds_read_b128 v[228:231], v168 offset:21504
	ds_read_b128 v[232:235], v168 offset:22528
	ds_read_b128 v[236:239], v168 offset:23552
	global_load_lds_dwordx4 v[162:163], off
	v_lshl_add_u64 v[244:245], v[242:243], 0, v[144:145]
	s_add_i32 m0, s3, 0x2000
	v_lshl_add_u64 v[246:247], v[242:243], 0, s[74:75]
	s_add_i32 s3, s8, s1
	global_load_lds_dwordx4 v[244:245], off
	v_lshl_add_u64 v[248:249], v[246:247], 0, v[128:129]
	s_mov_b32 m0, s3
	v_lshl_add_u64 v[246:247], v[246:247], 0, v[144:145]
	global_load_lds_dwordx4 v[248:249], off
	s_add_i32 m0, s3, 0x2000
	v_lshl_add_u64 v[248:249], v[240:241], 0, v[146:147]
	global_load_lds_dwordx4 v[246:247], off
	v_lshl_add_u64 v[246:247], v[240:241], 0, v[148:149]
	s_mov_b32 m0, s14
	s_nop 0
	global_load_lds_dwordx4 v[246:247], off
	s_mov_b32 m0, s15
	s_nop 0
	global_load_lds_dwordx4 v[248:249], off
	s_waitcnt vmcnt(8) lgkmcnt(0)
	s_barrier
; #define PG8_STAGE(bufoff, gbase, voff) do { _Pragma("unroll") for (int _i = 0; _i < 2; ++_i) \
;         __builtin_amdgcn_global_load_lds((const unsigned*)((const char*)(gbase) + (voff)[_i]), (PG8_LAS unsigned*)(lds + (bufoff) + ldsw + _i * 8192), 16, 0, 0); } while (0)
; #define PG8_LDA(dst, b, h) do { _Pragma("unroll") for (int m = 0; m < 4; ++m) _Pragma("unroll") for (int k = 0; k < 2; ++k) dst[m][k] = *(const PG8_LAS bf16x8*)(lds + PG8_SA(b, h) + aoff + m * 2048 + k * 1024); } while (0)
; #define PG8_LDB(dst, b, h) do { _Pragma("unroll") for (int n = 0; n < 2; ++n) _Pragma("unroll") for (int k = 0; k < 2; ++k) dst[n][k] = *(const PG8_LAS bf16x8*)(lds + PG8_SB(b, h) + boff + n * 2048 + k * 1024); } while (0)
; #define PG8_MMA(ai, bj, At, Bt) do { __builtin_amdgcn_s_setprio(1); _Pragma("unroll") for (int m = 0; m < 4; ++m) _Pragma("unroll") for (int n = 0; n < 2; ++n) _Pragma("unroll") for (int k = 0; k < 2; ++k) \
;         acc[ai][bj][m][n] = __builtin_amdgcn_mfma_f32_16x16x32_bf16(Bt[n][k], At[m][k], acc[ai][bj][m][n], 0, 0, 0); __builtin_amdgcn_s_setprio(0); } while (0)
; #define PG8_WAIT_V(n) asm volatile("s_waitcnt vmcnt(" #n ")" ::: "memory")
; #define PG8_WAIT_L(n) asm volatile("s_waitcnt lgkmcnt(" #n ")" ::: "memory")
; #define PG8_BAR __builtin_amdgcn_s_barrier()
; #define PG8_SCHED __builtin_amdgcn_sched_barrier(0)
; template <class Epi, class Sched, bool ALIGN_EPI = false, bool SP2 = false>
; __device__ __forceinline__ void gemm_phase(PG8_LAS unsigned char* lds, const Gemm g, const Sched& S, const Epi& E, int tid_in) {
;     ...
;             PG8_WAIT_V(8); PG8_WAIT_L(0); PG8_BAR; PG8_MMA(1, 0, At, B0); PG8_MMA(1, 1, At, B1); PG8_BAR; PG8_SCHED;
;             PG8_LDB(B0, 1, 0); PG8_LDB(B1, 1, 1); PG8_SCHED; PG8_LDA(At, 1, 0); PG8_STAGE(PG8_SA(0, 1), a2 + hstep, voffA);
;             PG8_WAIT_V(8); PG8_WAIT_L(0); PG8_BAR; PG8_MMA(0, 0, At, B0); PG8_MMA(0, 1, At, B1); PG8_BAR; PG8_SCHED;
	v_mfma_f32_16x16x32_bf16 v[60:63], v[176:179], v[208:211], v[60:63]
	v_mfma_f32_16x16x32_bf16 v[56:59], v[184:187], v[208:211], v[56:59]
	v_mfma_f32_16x16x32_bf16 v[52:55], v[176:179], v[216:219], v[52:55]
	v_mfma_f32_16x16x32_bf16 v[44:47], v[184:187], v[216:219], v[44:47]
	v_mfma_f32_16x16x32_bf16 v[36:39], v[176:179], v[224:227], v[36:39]
	v_mfma_f32_16x16x32_bf16 v[28:31], v[184:187], v[224:227], v[28:31]
	v_mfma_f32_16x16x32_bf16 v[20:23], v[176:179], v[232:235], v[20:23]
	v_mfma_f32_16x16x32_bf16 v[12:15], v[184:187], v[232:235], v[12:15]
	v_mfma_f32_16x16x32_bf16 v[60:63], v[180:183], v[212:215], v[60:63]
	v_mfma_f32_16x16x32_bf16 v[56:59], v[188:191], v[212:215], v[56:59]
	v_mfma_f32_16x16x32_bf16 v[52:55], v[180:183], v[220:223], v[52:55]
	v_mfma_f32_16x16x32_bf16 v[44:47], v[188:191], v[220:223], v[44:47]
	v_mfma_f32_16x16x32_bf16 v[36:39], v[180:183], v[228:231], v[36:39]
	v_mfma_f32_16x16x32_bf16 v[28:31], v[188:191], v[228:231], v[28:31]
	v_mfma_f32_16x16x32_bf16 v[20:23], v[180:183], v[236:239], v[20:23]
	v_mfma_f32_16x16x32_bf16 v[12:15], v[188:191], v[236:239], v[12:15]
	v_mfma_f32_16x16x32_bf16 v[48:51], v[192:195], v[208:211], v[48:51]
	v_mfma_f32_16x16x32_bf16 v[40:43], v[200:203], v[208:211], v[40:43]
	v_mfma_f32_16x16x32_bf16 v[32:35], v[192:195], v[216:219], v[32:35]
	v_mfma_f32_16x16x32_bf16 v[24:27], v[200:203], v[216:219], v[24:27]
	v_mfma_f32_16x16x32_bf16 v[16:19], v[192:195], v[224:227], v[16:19]
	v_mfma_f32_16x16x32_bf16 v[8:11], v[200:203], v[224:227], v[8:11]
	v_mfma_f32_16x16x32_bf16 v[4:7], v[192:195], v[232:235], v[4:7]
	v_mfma_f32_16x16x32_bf16 v[0:3], v[200:203], v[232:235], v[0:3]
	v_mfma_f32_16x16x32_bf16 v[48:51], v[196:199], v[212:215], v[48:51]
	v_mfma_f32_16x16x32_bf16 v[40:43], v[204:207], v[212:215], v[40:43]
	v_mfma_f32_16x16x32_bf16 v[32:35], v[196:199], v[220:223], v[32:35]
	v_mfma_f32_16x16x32_bf16 v[24:27], v[204:207], v[220:223], v[24:27]
	v_mfma_f32_16x16x32_bf16 v[16:19], v[196:199], v[228:231], v[16:19]
	v_mfma_f32_16x16x32_bf16 v[8:11], v[204:207], v[228:231], v[8:11]
	v_mfma_f32_16x16x32_bf16 v[4:7], v[196:199], v[236:239], v[4:7]
	v_mfma_f32_16x16x32_bf16 v[0:3], v[204:207], v[236:239], v[0:3]
	s_barrier
	s_add_i32 s3, 0, 0x18000
	v_add_u32_e32 v169, s3, v166
	s_add_i32 s8, 0, 0x1c000
	ds_read_b128 v[176:179], v169
	ds_read_b128 v[180:183], v169 offset:1024
	ds_read_b128 v[184:187], v169 offset:2048
	ds_read_b128 v[188:191], v169 offset:3072
	v_add_u32_e32 v169, s8, v166
	ds_read_b128 v[192:195], v169
	ds_read_b128 v[196:199], v169 offset:1024
	ds_read_b128 v[200:203], v169 offset:2048
	ds_read_b128 v[204:207], v169 offset:3072
	v_lshl_add_u64 v[240:241], v[240:241], 0, s[74:75]
	s_mov_b32 m0, s16
	v_lshl_add_u64 v[250:251], v[240:241], 0, v[148:149]
	ds_read_b128 v[208:211], v168 offset:32768
	ds_read_b128 v[212:215], v168 offset:33792
	ds_read_b128 v[216:219], v168 offset:34816
	ds_read_b128 v[220:223], v168 offset:35840
	ds_read_b128 v[224:227], v168 offset:36864
	ds_read_b128 v[228:231], v168 offset:37888
	ds_read_b128 v[232:235], v168 offset:38912
	ds_read_b128 v[236:239], v168 offset:39936
	global_load_lds_dwordx4 v[250:251], off
	v_lshl_add_u64 v[240:241], v[240:241], 0, v[146:147]
	s_mov_b32 m0, s17
	s_nop 0
	global_load_lds_dwordx4 v[240:241], off
	s_waitcnt vmcnt(8) lgkmcnt(0)
	s_barrier
	v_mfma_f32_16x16x32_bf16 v[124:127], v[176:179], v[208:211], v[124:127]
	v_mfma_f32_16x16x32_bf16 v[120:123], v[184:187], v[208:211], v[120:123]
	v_mfma_f32_16x16x32_bf16 v[116:119], v[176:179], v[216:219], v[116:119]
	v_mfma_f32_16x16x32_bf16 v[108:111], v[184:187], v[216:219], v[108:111]
	v_mfma_f32_16x16x32_bf16 v[100:103], v[176:179], v[224:227], v[100:103]
	v_mfma_f32_16x16x32_bf16 v[92:95], v[184:187], v[224:227], v[92:95]
	v_mfma_f32_16x16x32_bf16 v[84:87], v[176:179], v[232:235], v[84:87]
	v_mfma_f32_16x16x32_bf16 v[76:79], v[184:187], v[232:235], v[76:79]
	v_mfma_f32_16x16x32_bf16 v[124:127], v[180:183], v[212:215], v[124:127]
	v_mfma_f32_16x16x32_bf16 v[120:123], v[188:191], v[212:215], v[120:123]
	v_mfma_f32_16x16x32_bf16 v[116:119], v[180:183], v[220:223], v[116:119]
	v_mfma_f32_16x16x32_bf16 v[108:111], v[188:191], v[220:223], v[108:111]
	v_mfma_f32_16x16x32_bf16 v[100:103], v[180:183], v[228:231], v[100:103]
	v_mfma_f32_16x16x32_bf16 v[92:95], v[188:191], v[228:231], v[92:95]
	v_mfma_f32_16x16x32_bf16 v[84:87], v[180:183], v[236:239], v[84:87]
	v_mfma_f32_16x16x32_bf16 v[76:79], v[188:191], v[236:239], v[76:79]
	v_mfma_f32_16x16x32_bf16 v[112:115], v[192:195], v[208:211], v[112:115]
	v_mfma_f32_16x16x32_bf16 v[104:107], v[200:203], v[208:211], v[104:107]
	v_mfma_f32_16x16x32_bf16 v[96:99], v[192:195], v[216:219], v[96:99]
	v_mfma_f32_16x16x32_bf16 v[88:91], v[200:203], v[216:219], v[88:91]
	v_mfma_f32_16x16x32_bf16 v[80:83], v[192:195], v[224:227], v[80:83]
	v_mfma_f32_16x16x32_bf16 v[72:75], v[200:203], v[224:227], v[72:75]
	v_mfma_f32_16x16x32_bf16 v[68:71], v[192:195], v[232:235], v[68:71]
	v_mfma_f32_16x16x32_bf16 v[64:67], v[200:203], v[232:235], v[64:67]
	v_mfma_f32_16x16x32_bf16 v[112:115], v[196:199], v[212:215], v[112:115]
	v_mfma_f32_16x16x32_bf16 v[104:107], v[204:207], v[212:215], v[104:107]
	v_mfma_f32_16x16x32_bf16 v[96:99], v[196:199], v[220:223], v[96:99]
	v_mfma_f32_16x16x32_bf16 v[88:91], v[204:207], v[220:223], v[88:91]
	v_mfma_f32_16x16x32_bf16 v[80:83], v[196:199], v[228:231], v[80:83]
	v_mfma_f32_16x16x32_bf16 v[72:75], v[204:207], v[228:231], v[72:75]
	v_mfma_f32_16x16x32_bf16 v[68:71], v[196:199], v[236:239], v[68:71]
	v_mfma_f32_16x16x32_bf16 v[64:67], v[204:207], v[236:239], v[64:67]
	s_barrier
; #define PG8_STAGE(bufoff, gbase, voff) do { _Pragma("unroll") for (int _i = 0; _i < 2; ++_i) \
;         __builtin_amdgcn_global_load_lds((const unsigned*)((const char*)(gbase) + (voff)[_i]), (PG8_LAS unsigned*)(lds + (bufoff) + ldsw + _i * 8192), 16, 0, 0); } while (0)
; #define PG8_LDA(dst, b, h) do { _Pragma("unroll") for (int m = 0; m < 4; ++m) _Pragma("unroll") for (int k = 0; k < 2; ++k) dst[m][k] = *(const PG8_LAS bf16x8*)(lds + PG8_SA(b, h) + aoff + m * 2048 + k * 1024); } while (0)
; #define PG8_MMA(ai, bj, At, Bt) do { __builtin_amdgcn_s_setprio(1); _Pragma("unroll") for (int m = 0; m < 4; ++m) _Pragma("unroll") for (int n = 0; n < 2; ++n) _Pragma("unroll") for (int k = 0; k < 2; ++k) \
;         acc[ai][bj][m][n] = __builtin_amdgcn_mfma_f32_16x16x32_bf16(Bt[n][k], At[m][k], acc[ai][bj][m][n], 0, 0, 0); __builtin_amdgcn_s_setprio(0); } while (0)
; #define PG8_WAIT_V(n) asm volatile("s_waitcnt vmcnt(" #n ")" ::: "memory")
; #define PG8_WAIT_L(n) asm volatile("s_waitcnt lgkmcnt(" #n ")" ::: "memory")
; #define PG8_BAR __builtin_amdgcn_s_barrier()
; #define PG8_SCHED __builtin_amdgcn_sched_barrier(0)
; template <class Epi, class Sched, bool ALIGN_EPI = false, bool SP2 = false>
; __device__ __forceinline__ void gemm_phase(PG8_LAS unsigned char* lds, const Gemm g, const Sched& S, const Epi& E, int tid_in) {
;     ...
;         for (int t = 0; t < nt; t += 2) {
;             const bool last = (t == nt - 2);
;             const char* a1 = cA + (size_t)(t + 1) * kstep;
;             const char* a2 = last ? nA : cA + (size_t)(t + 2) * kstep; const char* b2 = last ? nB : cB + (size_t)(t + 2) * kstep;
;             const char* a3 = a2 + kstep; const char* b3 = b2 + kstep;
;     ...
;             PG8_LDA(At, 1, 1); PG8_STAGE(PG8_SB(1, 0), b3, voffB); PG8_STAGE(PG8_SB(1, 1), b3 + hstep, voffB); PG8_STAGE(PG8_SA(1, 0), a3, voffA);
;             PG8_WAIT_V(8); PG8_WAIT_L(0); PG8_BAR; PG8_MMA(1, 0, At, B0); PG8_MMA(1, 1, At, B1); PG8_BAR; PG8_SCHED;
;     ...
;         if constexpr (ALIGN_EPI) { if (wr == 0) PG8_BAR; }
	s_add_i32 s3, s3, s1
	v_lshl_add_u64 v[162:163], v[162:163], 0, s[70:71]
	s_mov_b32 m0, s3
	ds_read_b128 v[208:211], v168 offset:49152
	ds_read_b128 v[212:215], v168 offset:50176
	ds_read_b128 v[216:219], v168 offset:51200
	ds_read_b128 v[220:223], v168 offset:52224
	ds_read_b128 v[224:227], v168 offset:53248
	ds_read_b128 v[228:231], v168 offset:54272
	ds_read_b128 v[232:235], v168 offset:55296
	ds_read_b128 v[236:239], v168 offset:56320
	global_load_lds_dwordx4 v[162:163], off
	v_lshl_add_u64 v[162:163], v[244:245], 0, s[70:71]
	s_add_i32 m0, s3, 0x2000
	s_add_i32 s3, s8, s1
	global_load_lds_dwordx4 v[162:163], off
	v_lshl_add_u64 v[162:163], v[242:243], 0, s[60:61]
	v_lshl_add_u64 v[240:241], v[162:163], 0, v[128:129]
	s_mov_b32 m0, s3
	v_lshl_add_u64 v[162:163], v[162:163], 0, v[144:145]
	global_load_lds_dwordx4 v[240:241], off
	s_add_i32 m0, s3, 0x2000
	s_nop 0
	global_load_lds_dwordx4 v[162:163], off
	v_lshl_add_u64 v[162:163], v[246:247], 0, s[70:71]
	s_mov_b32 m0, s18
	s_nop 0
	global_load_lds_dwordx4 v[162:163], off
	v_lshl_add_u64 v[162:163], v[248:249], 0, s[70:71]
	s_mov_b32 m0, s19
	s_nop 0
	global_load_lds_dwordx4 v[162:163], off
	s_waitcnt vmcnt(8) lgkmcnt(0)
	s_barrier
	v_mfma_f32_16x16x32_bf16 v[60:63], v[176:179], v[208:211], v[60:63]
	v_mfma_f32_16x16x32_bf16 v[56:59], v[184:187], v[208:211], v[56:59]
	v_mfma_f32_16x16x32_bf16 v[52:55], v[176:179], v[216:219], v[52:55]
	v_mfma_f32_16x16x32_bf16 v[44:47], v[184:187], v[216:219], v[44:47]
	v_mfma_f32_16x16x32_bf16 v[36:39], v[176:179], v[224:227], v[36:39]
	v_mfma_f32_16x16x32_bf16 v[28:31], v[184:187], v[224:227], v[28:31]
	v_mfma_f32_16x16x32_bf16 v[20:23], v[176:179], v[232:235], v[20:23]
	v_mfma_f32_16x16x32_bf16 v[12:15], v[184:187], v[232:235], v[12:15]
	v_mfma_f32_16x16x32_bf16 v[60:63], v[180:183], v[212:215], v[60:63]
	v_mfma_f32_16x16x32_bf16 v[56:59], v[188:191], v[212:215], v[56:59]
	v_mfma_f32_16x16x32_bf16 v[52:55], v[180:183], v[220:223], v[52:55]
	v_mfma_f32_16x16x32_bf16 v[44:47], v[188:191], v[220:223], v[44:47]
	v_mfma_f32_16x16x32_bf16 v[36:39], v[180:183], v[228:231], v[36:39]
	v_mfma_f32_16x16x32_bf16 v[28:31], v[188:191], v[228:231], v[28:31]
	v_mfma_f32_16x16x32_bf16 v[20:23], v[180:183], v[236:239], v[20:23]
	v_mfma_f32_16x16x32_bf16 v[12:15], v[188:191], v[236:239], v[12:15]
	v_mfma_f32_16x16x32_bf16 v[48:51], v[192:195], v[208:211], v[48:51]
	v_mfma_f32_16x16x32_bf16 v[40:43], v[200:203], v[208:211], v[40:43]
	v_mfma_f32_16x16x32_bf16 v[32:35], v[192:195], v[216:219], v[32:35]
	v_mfma_f32_16x16x32_bf16 v[24:27], v[200:203], v[216:219], v[24:27]
	v_mfma_f32_16x16x32_bf16 v[16:19], v[192:195], v[224:227], v[16:19]
	v_mfma_f32_16x16x32_bf16 v[8:11], v[200:203], v[224:227], v[8:11]
	v_mfma_f32_16x16x32_bf16 v[4:7], v[192:195], v[232:235], v[4:7]
	v_mfma_f32_16x16x32_bf16 v[0:3], v[200:203], v[232:235], v[0:3]
	v_mfma_f32_16x16x32_bf16 v[48:51], v[196:199], v[212:215], v[48:51]
	v_mfma_f32_16x16x32_bf16 v[40:43], v[204:207], v[212:215], v[40:43]
	v_mfma_f32_16x16x32_bf16 v[32:35], v[196:199], v[220:223], v[32:35]
	v_mfma_f32_16x16x32_bf16 v[24:27], v[204:207], v[220:223], v[24:27]
	v_mfma_f32_16x16x32_bf16 v[16:19], v[196:199], v[228:231], v[16:19]
	v_mfma_f32_16x16x32_bf16 v[8:11], v[204:207], v[228:231], v[8:11]
	v_mfma_f32_16x16x32_bf16 v[4:7], v[196:199], v[236:239], v[4:7]
	v_mfma_f32_16x16x32_bf16 v[0:3], v[204:207], v[236:239], v[0:3]
	s_barrier
	s_add_i32 s2, s2, 2
	v_lshl_add_u64 v[160:161], v[160:161], 0, s[82:83]
	s_cmpk_gt_u32 s2, 0x55
	v_mov_b64_e32 v[162:163], v[164:165]
	s_cbranch_scc0 .LBB0_683
	s_and_b64 vcc, exec, s[12:13]
	s_cbranch_vccz .LBB0_686
	s_barrier
